# GEMM loops: temp-address LDS-DMA loads use SGPR base + 32-bit VGPR offset (8 of 16 64-bit address adds per iteration removed)
# speedup vs baseline: 1.0209x; 1.0052x over previous
; #define PG8_STAGE(bufoff, gbase, voff) do { _Pragma("unroll") for (int _i = 0; _i < 2; ++_i) \
;         __builtin_amdgcn_global_load_lds((const unsigned*)((const char*)(gbase) + (voff)[_i]), (LAS unsigned*)(lds + (bufoff) + ldsw + _i * 8192), 16, 0, 0); } while (0)
; #define PG8_LDA(dst, b, h) do { _Pragma("unroll") for (int m = 0; m < 4; ++m) _Pragma("unroll") for (int k = 0; k < 2; ++k) dst[m][k] = *(const LAS bf16x8*)(lds + PG8_SA(b, h) + aoff + m * 2048 + k * 1024); } while (0)
; #define PG8_LDB(dst, b, h) do { _Pragma("unroll") for (int n = 0; n < 2; ++n) _Pragma("unroll") for (int k = 0; k < 2; ++k) dst[n][k] = *(const LAS bf16x8*)(lds + PG8_SB(b, h) + boff + n * 2048 + k * 1024); } while (0)
; #define PG8_WAIT_V(n) asm volatile("s_waitcnt vmcnt(" #n ")" ::: "memory")
; #define PG8_WAIT_L(n) asm volatile("s_waitcnt lgkmcnt(" #n ")" ::: "memory")
; #define PG8_BAR __builtin_amdgcn_s_barrier()
; #define PG8_SCHED __builtin_amdgcn_sched_barrier(0)
; template <class Epi, class Sched, bool F8 = false>
; __device__ __forceinline__ void gemm_phase(LAS unsigned char* lds, const Gemm g, const Sched& S, const Epi& E) {
;     ...
;         for (int t = 0; t < nt; t += 2) {
;             const bool last = (t == nt - 2);
;             const char* a1 = cA + (size_t)(t + 1) * kstep;
;             const char* a2 = last ? nA : cA + (size_t)(t + 2) * kstep; const char* b2 = last ? nB : cB + (size_t)(t + 2) * kstep;
;             const char* a3 = a2 + kstep; const char* b3 = b2 + kstep;
;             PG8_LDB(B0, 0, 0); PG8_LDB(B1, 0, 1); PG8_SCHED; PG8_LDA(At, 0, 0); PG8_STAGE(PG8_SA(1, 1), a1 + hstepA, voffA);
;             PG8_WAIT_V(8); PG8_WAIT_L(0); PG8_BAR; PG8_MMA(0, 0, At, B0); PG8_MMA(0, 1, At, B1); PG8_BAR; PG8_SCHED;
;             PG8_LDA(At, 0, 1); PG8_STAGE(PG8_SB(0, 0), b2, voffB); PG8_STAGE(PG8_SB(0, 1), b2 + hstepB, voffB); PG8_STAGE(PG8_SA(0, 0), a2, voffA);
;             PG8_WAIT_V(8); PG8_WAIT_L(0); PG8_BAR; PG8_MMA(1, 0, At, B0); PG8_MMA(1, 1, At, B1); PG8_BAR; PG8_SCHED;
;             PG8_LDB(B0, 1, 0); PG8_LDB(B1, 1, 1); PG8_SCHED; PG8_LDA(At, 1, 0); PG8_STAGE(PG8_SA(0, 1), a2 + hstepA, voffA);
;             PG8_WAIT_V(8); PG8_WAIT_L(0); PG8_BAR; PG8_MMA(0, 0, At, B0); PG8_MMA(0, 1, At, B1); PG8_BAR; PG8_SCHED;
.LBB0_144:
	ds_read_b128 v[72:75], v170
	ds_read_b128 v[76:79], v170 offset:1024
	ds_read_b128 v[80:83], v170 offset:2048
	ds_read_b128 v[88:91], v170 offset:3072
	ds_read_b128 v[162:165], v171
	ds_read_b128 v[174:177], v171 offset:1024
	ds_read_b128 v[178:181], v171 offset:2048
	ds_read_b128 v[182:185], v171 offset:3072
	s_add_u32 s30, s26, 0xfff80080
	s_addc_u32 s31, s27, -1
	s_cmp_eq_u32 s50, 28
	s_cselect_b32 s35, s7, s31
	s_cselect_b32 s34, s19, s30
	s_cselect_b32 s31, s17, s49
	s_cselect_b32 s30, s36, s37
	s_add_i32 m0, s29, 0xc000
	ds_read_b128 v[192:195], v172
	ds_read_b128 v[196:199], v172 offset:1024
	ds_read_b128 v[200:203], v172 offset:2048
	ds_read_b128 v[204:207], v172 offset:3072
	ds_read_b128 v[208:211], v172 offset:4096
	ds_read_b128 v[212:215], v172 offset:5120
	ds_read_b128 v[216:219], v172 offset:6144
	ds_read_b128 v[220:223], v172 offset:7168
	global_load_lds_dwordx4 v152, s[26:27]
	s_add_i32 m0, s29, 0xe000
	s_nop 0
	global_load_lds_dwordx4 v154, s[26:27]
	s_waitcnt vmcnt(8)
	s_waitcnt lgkmcnt(0)
	s_barrier
	s_setprio 1
	s_waitcnt lgkmcnt(0)
	v_mfma_f32_16x16x32_bf16 v[140:143], v[72:75], v[192:195], v[140:143]
	v_mfma_f32_16x16x32_bf16 v[136:139], v[80:83], v[192:195], v[136:139]
	v_mfma_f32_16x16x32_bf16 v[124:127], v[72:75], v[200:203], v[124:127]
	v_mfma_f32_16x16x32_bf16 v[120:123], v[80:83], v[200:203], v[120:123]
	v_mfma_f32_16x16x32_bf16 v[108:111], v[72:75], v[208:211], v[108:111]
	v_mfma_f32_16x16x32_bf16 v[104:107], v[80:83], v[208:211], v[104:107]
	v_mfma_f32_16x16x32_bf16 v[92:95], v[72:75], v[216:219], v[92:95]
	v_mfma_f32_16x16x32_bf16 v[84:87], v[80:83], v[216:219], v[84:87]
	v_mfma_f32_16x16x32_bf16 v[140:143], v[76:79], v[196:199], v[140:143]
	v_mfma_f32_16x16x32_bf16 v[136:139], v[88:91], v[196:199], v[136:139]
	v_mfma_f32_16x16x32_bf16 v[124:127], v[76:79], v[204:207], v[124:127]
	v_mfma_f32_16x16x32_bf16 v[120:123], v[88:91], v[204:207], v[120:123]
	v_mfma_f32_16x16x32_bf16 v[108:111], v[76:79], v[212:215], v[108:111]
	v_mfma_f32_16x16x32_bf16 v[104:107], v[88:91], v[212:215], v[104:107]
	v_mfma_f32_16x16x32_bf16 v[92:95], v[76:79], v[220:223], v[92:95]
	v_mfma_f32_16x16x32_bf16 v[84:87], v[88:91], v[220:223], v[84:87]
	s_setprio 0
	s_setprio 1
	v_mfma_f32_16x16x32_bf16 v[132:135], v[162:165], v[192:195], v[132:135]
	v_mfma_f32_16x16x32_bf16 v[128:131], v[178:181], v[192:195], v[128:131]
	v_mfma_f32_16x16x32_bf16 v[116:119], v[162:165], v[200:203], v[116:119]
	v_mfma_f32_16x16x32_bf16 v[112:115], v[178:181], v[200:203], v[112:115]
	v_mfma_f32_16x16x32_bf16 v[100:103], v[162:165], v[208:211], v[100:103]
	v_mfma_f32_16x16x32_bf16 v[96:99], v[178:181], v[208:211], v[96:99]
	v_mfma_f32_16x16x32_bf16 v[68:71], v[162:165], v[216:219], v[68:71]
	v_mfma_f32_16x16x32_bf16 v[64:67], v[178:181], v[216:219], v[64:67]
	v_mfma_f32_16x16x32_bf16 v[132:135], v[174:177], v[196:199], v[132:135]
	v_mfma_f32_16x16x32_bf16 v[128:131], v[182:185], v[196:199], v[128:131]
	v_mfma_f32_16x16x32_bf16 v[116:119], v[174:177], v[204:207], v[116:119]
	v_mfma_f32_16x16x32_bf16 v[112:115], v[182:185], v[204:207], v[112:115]
	v_mfma_f32_16x16x32_bf16 v[100:103], v[174:177], v[212:215], v[100:103]
	v_mfma_f32_16x16x32_bf16 v[96:99], v[182:185], v[212:215], v[96:99]
	v_mfma_f32_16x16x32_bf16 v[68:71], v[174:177], v[220:223], v[68:71]
	v_mfma_f32_16x16x32_bf16 v[64:67], v[182:185], v[220:223], v[64:67]
	s_setprio 0
	s_barrier
	s_add_i32 s51, s47, s38
	v_lshl_add_u64 v[166:167], s[30:31], 0, v[146:147]
	s_mov_b32 m0, s51
	ds_read_b128 v[192:195], v172 offset:16384
	ds_read_b128 v[196:199], v172 offset:17408
	ds_read_b128 v[200:203], v172 offset:18432
	ds_read_b128 v[204:207], v172 offset:19456
	ds_read_b128 v[208:211], v172 offset:20480
	ds_read_b128 v[212:215], v172 offset:21504
	ds_read_b128 v[216:219], v172 offset:22528
	ds_read_b128 v[220:223], v172 offset:23552
	global_load_lds_dwordx4 v[166:167], off
	s_add_i32 m0, s51, 0x2000
	s_add_u32 s56, s30, 0x80000
	v_lshl_add_u64 v[188:189], s[30:31], 0, v[150:151]
	s_addc_u32 s57, s31, 0
	s_add_i32 s51, s48, s38
	global_load_lds_dwordx4 v[188:189], off
	s_mov_b32 m0, s51
	v_lshl_add_u64 v[226:227], s[34:35], 0, v[148:149]
	global_load_lds_dwordx4 v146, s[56:57]
	s_add_i32 m0, s51, 0x2000
	s_nop 0
	global_load_lds_dwordx4 v150, s[56:57]
	v_lshl_add_u64 v[224:225], s[34:35], 0, v[144:145]
	s_mov_b32 m0, s29
	s_nop 0
	global_load_lds_dwordx4 v[224:225], off
	s_mov_b32 m0, s39
	s_nop 0
	global_load_lds_dwordx4 v[226:227], off
	s_waitcnt vmcnt(8)
	s_waitcnt lgkmcnt(0)
	s_barrier
	s_setprio 1
	s_waitcnt lgkmcnt(0)
	v_mfma_f32_16x16x32_bf16 v[60:63], v[72:75], v[192:195], v[60:63]
	v_mfma_f32_16x16x32_bf16 v[56:59], v[80:83], v[192:195], v[56:59]
	v_mfma_f32_16x16x32_bf16 v[44:47], v[72:75], v[200:203], v[44:47]
	v_mfma_f32_16x16x32_bf16 v[40:43], v[80:83], v[200:203], v[40:43]
	v_mfma_f32_16x16x32_bf16 v[28:31], v[72:75], v[208:211], v[28:31]
	v_mfma_f32_16x16x32_bf16 v[24:27], v[80:83], v[208:211], v[24:27]
	v_mfma_f32_16x16x32_bf16 v[12:15], v[72:75], v[216:219], v[12:15]
	v_mfma_f32_16x16x32_bf16 v[8:11], v[80:83], v[216:219], v[8:11]
	v_mfma_f32_16x16x32_bf16 v[60:63], v[76:79], v[196:199], v[60:63]
	v_mfma_f32_16x16x32_bf16 v[56:59], v[88:91], v[196:199], v[56:59]
	v_mfma_f32_16x16x32_bf16 v[44:47], v[76:79], v[204:207], v[44:47]
	v_mfma_f32_16x16x32_bf16 v[40:43], v[88:91], v[204:207], v[40:43]
	v_mfma_f32_16x16x32_bf16 v[28:31], v[76:79], v[212:215], v[28:31]
	v_mfma_f32_16x16x32_bf16 v[24:27], v[88:91], v[212:215], v[24:27]
	v_mfma_f32_16x16x32_bf16 v[12:15], v[76:79], v[220:223], v[12:15]
	v_mfma_f32_16x16x32_bf16 v[8:11], v[88:91], v[220:223], v[8:11]
	s_setprio 0
	s_setprio 1
	v_mfma_f32_16x16x32_bf16 v[52:55], v[162:165], v[192:195], v[52:55]
	v_mfma_f32_16x16x32_bf16 v[48:51], v[178:181], v[192:195], v[48:51]
	v_mfma_f32_16x16x32_bf16 v[36:39], v[162:165], v[200:203], v[36:39]
	v_mfma_f32_16x16x32_bf16 v[32:35], v[178:181], v[200:203], v[32:35]
	v_mfma_f32_16x16x32_bf16 v[20:23], v[162:165], v[208:211], v[20:23]
	v_mfma_f32_16x16x32_bf16 v[16:19], v[178:181], v[208:211], v[16:19]
	v_mfma_f32_16x16x32_bf16 v[4:7], v[162:165], v[216:219], v[4:7]
	v_mfma_f32_16x16x32_bf16 v[0:3], v[178:181], v[216:219], v[0:3]
	v_mfma_f32_16x16x32_bf16 v[52:55], v[174:177], v[196:199], v[52:55]
	v_mfma_f32_16x16x32_bf16 v[48:51], v[182:185], v[196:199], v[48:51]
	v_mfma_f32_16x16x32_bf16 v[36:39], v[174:177], v[204:207], v[36:39]
	v_mfma_f32_16x16x32_bf16 v[32:35], v[182:185], v[204:207], v[32:35]
	v_mfma_f32_16x16x32_bf16 v[20:23], v[174:177], v[212:215], v[20:23]
	v_mfma_f32_16x16x32_bf16 v[16:19], v[182:185], v[212:215], v[16:19]
	v_mfma_f32_16x16x32_bf16 v[4:7], v[174:177], v[220:223], v[4:7]
	v_mfma_f32_16x16x32_bf16 v[0:3], v[182:185], v[220:223], v[0:3]
	s_setprio 0
	s_barrier
; #define PG8_STAGE(bufoff, gbase, voff) do { _Pragma("unroll") for (int _i = 0; _i < 2; ++_i) \
;         __builtin_amdgcn_global_load_lds((const unsigned*)((const char*)(gbase) + (voff)[_i]), (LAS unsigned*)(lds + (bufoff) + ldsw + _i * 8192), 16, 0, 0); } while (0)
; #define PG8_LDA(dst, b, h) do { _Pragma("unroll") for (int m = 0; m < 4; ++m) _Pragma("unroll") for (int k = 0; k < 2; ++k) dst[m][k] = *(const LAS bf16x8*)(lds + PG8_SA(b, h) + aoff + m * 2048 + k * 1024); } while (0)
; #define PG8_LDB(dst, b, h) do { _Pragma("unroll") for (int n = 0; n < 2; ++n) _Pragma("unroll") for (int k = 0; k < 2; ++k) dst[n][k] = *(const LAS bf16x8*)(lds + PG8_SB(b, h) + boff + n * 2048 + k * 1024); } while (0)
; #define PG8_WAIT_V(n) asm volatile("s_waitcnt vmcnt(" #n ")" ::: "memory")
; #define PG8_WAIT_L(n) asm volatile("s_waitcnt lgkmcnt(" #n ")" ::: "memory")
; #define PG8_BAR __builtin_amdgcn_s_barrier()
; #define PG8_SCHED __builtin_amdgcn_sched_barrier(0)
; template <class Epi, class Sched, bool F8 = false>
; __device__ __forceinline__ void gemm_phase(LAS unsigned char* lds, const Gemm g, const Sched& S, const Epi& E) {
;     ...
;             PG8_LDB(B0, 1, 0); PG8_LDB(B1, 1, 1); PG8_SCHED; PG8_LDA(At, 1, 0); PG8_STAGE(PG8_SA(0, 1), a2 + hstepA, voffA);
;             PG8_WAIT_V(8); PG8_WAIT_L(0); PG8_BAR; PG8_MMA(0, 0, At, B0); PG8_MMA(0, 1, At, B1); PG8_BAR; PG8_SCHED;
;             PG8_LDA(At, 1, 1); PG8_STAGE(PG8_SB(1, 0), b3, voffB); PG8_STAGE(PG8_SB(1, 1), b3 + hstepB, voffB); PG8_STAGE(PG8_SA(1, 0), a3, voffA);
;             PG8_WAIT_V(8); PG8_WAIT_L(0); PG8_BAR; PG8_MMA(1, 0, At, B0); PG8_MMA(1, 1, At, B1); PG8_BAR; PG8_SCHED;
;         }
	s_add_i32 s51, 0, 0x18000
	s_add_i32 s53, 0, 0x1c000
	v_add_u32_e32 v88, s51, v168
	v_add_u32_e32 v173, s53, v168
	ds_read_b128 v[72:75], v88
	ds_read_b128 v[76:79], v88 offset:1024
	ds_read_b128 v[80:83], v88 offset:2048
	ds_read_b128 v[88:91], v88 offset:3072
	ds_read_b128 v[162:165], v173
	ds_read_b128 v[174:177], v173 offset:1024
	ds_read_b128 v[178:181], v173 offset:2048
	ds_read_b128 v[182:185], v173 offset:3072
	s_add_u32 s34, s34, 0x80000
	s_addc_u32 s35, s35, 0
	s_mov_b32 m0, s40
	ds_read_b128 v[192:195], v172 offset:32768
	ds_read_b128 v[196:199], v172 offset:33792
	ds_read_b128 v[200:203], v172 offset:34816
	ds_read_b128 v[204:207], v172 offset:35840
	ds_read_b128 v[208:211], v172 offset:36864
	ds_read_b128 v[212:215], v172 offset:37888
	ds_read_b128 v[216:219], v172 offset:38912
	ds_read_b128 v[220:223], v172 offset:39936
	global_load_lds_dwordx4 v144, s[34:35]
	s_mov_b32 m0, s41
	s_nop 0
	global_load_lds_dwordx4 v148, s[34:35]
	s_waitcnt vmcnt(8)
	s_waitcnt lgkmcnt(0)
	s_barrier
	s_setprio 1
	s_waitcnt lgkmcnt(0)
	v_mfma_f32_16x16x32_bf16 v[140:143], v[72:75], v[192:195], v[140:143]
	v_mfma_f32_16x16x32_bf16 v[136:139], v[80:83], v[192:195], v[136:139]
	v_mfma_f32_16x16x32_bf16 v[124:127], v[72:75], v[200:203], v[124:127]
	v_mfma_f32_16x16x32_bf16 v[120:123], v[80:83], v[200:203], v[120:123]
	v_mfma_f32_16x16x32_bf16 v[108:111], v[72:75], v[208:211], v[108:111]
	v_mfma_f32_16x16x32_bf16 v[104:107], v[80:83], v[208:211], v[104:107]
	v_mfma_f32_16x16x32_bf16 v[92:95], v[72:75], v[216:219], v[92:95]
	v_mfma_f32_16x16x32_bf16 v[84:87], v[80:83], v[216:219], v[84:87]
	v_mfma_f32_16x16x32_bf16 v[140:143], v[76:79], v[196:199], v[140:143]
	v_mfma_f32_16x16x32_bf16 v[136:139], v[88:91], v[196:199], v[136:139]
	v_mfma_f32_16x16x32_bf16 v[124:127], v[76:79], v[204:207], v[124:127]
	v_mfma_f32_16x16x32_bf16 v[120:123], v[88:91], v[204:207], v[120:123]
	v_mfma_f32_16x16x32_bf16 v[108:111], v[76:79], v[212:215], v[108:111]
	v_mfma_f32_16x16x32_bf16 v[104:107], v[88:91], v[212:215], v[104:107]
	v_mfma_f32_16x16x32_bf16 v[92:95], v[76:79], v[220:223], v[92:95]
	v_mfma_f32_16x16x32_bf16 v[84:87], v[88:91], v[220:223], v[84:87]
	s_setprio 0
	s_setprio 1
	v_mfma_f32_16x16x32_bf16 v[132:135], v[162:165], v[192:195], v[132:135]
	v_mfma_f32_16x16x32_bf16 v[128:131], v[178:181], v[192:195], v[128:131]
	v_mfma_f32_16x16x32_bf16 v[116:119], v[162:165], v[200:203], v[116:119]
	v_mfma_f32_16x16x32_bf16 v[112:115], v[178:181], v[200:203], v[112:115]
	v_mfma_f32_16x16x32_bf16 v[100:103], v[162:165], v[208:211], v[100:103]
	v_mfma_f32_16x16x32_bf16 v[96:99], v[178:181], v[208:211], v[96:99]
	v_mfma_f32_16x16x32_bf16 v[68:71], v[162:165], v[216:219], v[68:71]
	v_mfma_f32_16x16x32_bf16 v[64:67], v[178:181], v[216:219], v[64:67]
	v_mfma_f32_16x16x32_bf16 v[132:135], v[174:177], v[196:199], v[132:135]
	v_mfma_f32_16x16x32_bf16 v[128:131], v[182:185], v[196:199], v[128:131]
	v_mfma_f32_16x16x32_bf16 v[116:119], v[174:177], v[204:207], v[116:119]
	v_mfma_f32_16x16x32_bf16 v[112:115], v[182:185], v[204:207], v[112:115]
	v_mfma_f32_16x16x32_bf16 v[100:103], v[174:177], v[212:215], v[100:103]
	v_mfma_f32_16x16x32_bf16 v[96:99], v[182:185], v[212:215], v[96:99]
	v_mfma_f32_16x16x32_bf16 v[68:71], v[174:177], v[220:223], v[68:71]
	v_mfma_f32_16x16x32_bf16 v[64:67], v[182:185], v[220:223], v[64:67]
	s_setprio 0
	s_barrier
	s_add_i32 s34, s51, s38
	v_lshl_add_u64 v[166:167], v[166:167], 0, s[12:13]
	s_mov_b32 m0, s34
	ds_read_b128 v[192:195], v172 offset:49152
	ds_read_b128 v[196:199], v172 offset:50176
	ds_read_b128 v[200:203], v172 offset:51200
	ds_read_b128 v[204:207], v172 offset:52224
	ds_read_b128 v[208:211], v172 offset:53248
	ds_read_b128 v[212:215], v172 offset:54272
	ds_read_b128 v[216:219], v172 offset:55296
	ds_read_b128 v[220:223], v172 offset:56320
	global_load_lds_dwordx4 v[166:167], off
	s_add_i32 m0, s34, 0x2000
	s_add_u32 s30, s30, 0x80080
	v_lshl_add_u64 v[166:167], v[188:189], 0, s[12:13]
	s_addc_u32 s31, s31, 0
	s_add_i32 s34, s53, s38
	global_load_lds_dwordx4 v[166:167], off
	s_mov_b32 m0, s34
	s_nop 0
	global_load_lds_dwordx4 v146, s[30:31]
	s_add_i32 m0, s34, 0x2000
	s_nop 0
	global_load_lds_dwordx4 v150, s[30:31]
	v_lshl_add_u64 v[166:167], v[224:225], 0, s[12:13]
	s_mov_b32 m0, s43
	s_nop 0
	global_load_lds_dwordx4 v[166:167], off
	v_lshl_add_u64 v[166:167], v[226:227], 0, s[12:13]
	s_mov_b32 m0, s44
	s_nop 0
	global_load_lds_dwordx4 v[166:167], off
	s_waitcnt vmcnt(8)
	s_waitcnt lgkmcnt(0)
	s_barrier
	s_setprio 1
	s_waitcnt lgkmcnt(0)
	v_mfma_f32_16x16x32_bf16 v[60:63], v[72:75], v[192:195], v[60:63]
	v_mfma_f32_16x16x32_bf16 v[56:59], v[80:83], v[192:195], v[56:59]
	v_mfma_f32_16x16x32_bf16 v[44:47], v[72:75], v[200:203], v[44:47]
	v_mfma_f32_16x16x32_bf16 v[40:43], v[80:83], v[200:203], v[40:43]
	v_mfma_f32_16x16x32_bf16 v[28:31], v[72:75], v[208:211], v[28:31]
	v_mfma_f32_16x16x32_bf16 v[24:27], v[80:83], v[208:211], v[24:27]
	v_mfma_f32_16x16x32_bf16 v[12:15], v[72:75], v[216:219], v[12:15]
	v_mfma_f32_16x16x32_bf16 v[8:11], v[80:83], v[216:219], v[8:11]
	v_mfma_f32_16x16x32_bf16 v[60:63], v[76:79], v[196:199], v[60:63]
	v_mfma_f32_16x16x32_bf16 v[56:59], v[88:91], v[196:199], v[56:59]
	v_mfma_f32_16x16x32_bf16 v[44:47], v[76:79], v[204:207], v[44:47]
	v_mfma_f32_16x16x32_bf16 v[40:43], v[88:91], v[204:207], v[40:43]
	v_mfma_f32_16x16x32_bf16 v[28:31], v[76:79], v[212:215], v[28:31]
	v_mfma_f32_16x16x32_bf16 v[24:27], v[88:91], v[212:215], v[24:27]
	v_mfma_f32_16x16x32_bf16 v[12:15], v[76:79], v[220:223], v[12:15]
	v_mfma_f32_16x16x32_bf16 v[8:11], v[88:91], v[220:223], v[8:11]
	s_setprio 0
	s_setprio 1
	v_mfma_f32_16x16x32_bf16 v[52:55], v[162:165], v[192:195], v[52:55]
	v_mfma_f32_16x16x32_bf16 v[48:51], v[178:181], v[192:195], v[48:51]
	v_mfma_f32_16x16x32_bf16 v[36:39], v[162:165], v[200:203], v[36:39]
	v_mfma_f32_16x16x32_bf16 v[32:35], v[178:181], v[200:203], v[32:35]
	v_mfma_f32_16x16x32_bf16 v[20:23], v[162:165], v[208:211], v[20:23]
	v_mfma_f32_16x16x32_bf16 v[16:19], v[178:181], v[208:211], v[16:19]
	v_mfma_f32_16x16x32_bf16 v[4:7], v[162:165], v[216:219], v[4:7]
	v_mfma_f32_16x16x32_bf16 v[0:3], v[178:181], v[216:219], v[0:3]
	v_mfma_f32_16x16x32_bf16 v[52:55], v[174:177], v[196:199], v[52:55]
	v_mfma_f32_16x16x32_bf16 v[48:51], v[182:185], v[196:199], v[48:51]
	v_mfma_f32_16x16x32_bf16 v[36:39], v[174:177], v[204:207], v[36:39]
	v_mfma_f32_16x16x32_bf16 v[32:35], v[182:185], v[204:207], v[32:35]
	v_mfma_f32_16x16x32_bf16 v[20:23], v[174:177], v[212:215], v[20:23]
	v_mfma_f32_16x16x32_bf16 v[16:19], v[182:185], v[212:215], v[16:19]
	v_mfma_f32_16x16x32_bf16 v[4:7], v[174:177], v[220:223], v[4:7]
	v_mfma_f32_16x16x32_bf16 v[0:3], v[182:185], v[220:223], v[0:3]
	s_setprio 0
	s_barrier
	s_add_i32 s50, s50, 2
	s_add_u32 s26, s26, 0x100
	s_addc_u32 s27, s27, 0
	s_add_u32 s37, s37, 0x100
	s_addc_u32 s49, s49, 0
	s_cmp_gt_u32 s50, 29
	s_cbranch_scc0 .LBB0_144
	s_and_b64 vcc, exec, s[14:15]
	s_cbranch_vccz .LBB0_147
	s_barrier

; #define PG8_STAGE(bufoff, gbase, voff) do { _Pragma("unroll") for (int _i = 0; _i < 2; ++_i) \
;         __builtin_amdgcn_global_load_lds((const unsigned*)((const char*)(gbase) + (voff)[_i]), (LAS unsigned*)(lds + (bufoff) + ldsw + _i * 8192), 16, 0, 0); } while (0)
; #define PG8_LDA(dst, b, h) do { _Pragma("unroll") for (int m = 0; m < 4; ++m) _Pragma("unroll") for (int k = 0; k < 2; ++k) dst[m][k] = *(const LAS bf16x8*)(lds + PG8_SA(b, h) + aoff + m * 2048 + k * 1024); } while (0)
; #define PG8_LDB(dst, b, h) do { _Pragma("unroll") for (int n = 0; n < 2; ++n) _Pragma("unroll") for (int k = 0; k < 2; ++k) dst[n][k] = *(const LAS bf16x8*)(lds + PG8_SB(b, h) + boff + n * 2048 + k * 1024); } while (0)
; #define PG8_WAIT_V(n) asm volatile("s_waitcnt vmcnt(" #n ")" ::: "memory")
; #define PG8_WAIT_L(n) asm volatile("s_waitcnt lgkmcnt(" #n ")" ::: "memory")
; #define PG8_BAR __builtin_amdgcn_s_barrier()
; #define PG8_SCHED __builtin_amdgcn_sched_barrier(0)
; template <class Epi, class Sched, bool F8 = false>
; __device__ __forceinline__ void gemm_phase(LAS unsigned char* lds, const Gemm g, const Sched& S, const Epi& E) {
;     ...
;         for (int t = 0; t < nt; t += 2) {
;             const bool last = (t == nt - 2);
;             const char* a1 = cA + (size_t)(t + 1) * kstep;
;             const char* a2 = last ? nA : cA + (size_t)(t + 2) * kstep; const char* b2 = last ? nB : cB + (size_t)(t + 2) * kstep;
;             const char* a3 = a2 + kstep; const char* b3 = b2 + kstep;
;             PG8_LDB(B0, 0, 0); PG8_LDB(B1, 0, 1); PG8_SCHED; PG8_LDA(At, 0, 0); PG8_STAGE(PG8_SA(1, 1), a1 + hstepA, voffA);
;             PG8_WAIT_V(8); PG8_WAIT_L(0); PG8_BAR; PG8_MMA(0, 0, At, B0); PG8_MMA(0, 1, At, B1); PG8_BAR; PG8_SCHED;
;             PG8_LDA(At, 0, 1); PG8_STAGE(PG8_SB(0, 0), b2, voffB); PG8_STAGE(PG8_SB(0, 1), b2 + hstepB, voffB); PG8_STAGE(PG8_SA(0, 0), a2, voffA);
;             PG8_WAIT_V(8); PG8_WAIT_L(0); PG8_BAR; PG8_MMA(1, 0, At, B0); PG8_MMA(1, 1, At, B1); PG8_BAR; PG8_SCHED;
.LBB0_208:
	ds_read_b128 v[152:155], v189
	ds_read_b128 v[156:159], v189 offset:1024
	ds_read_b128 v[144:147], v189 offset:2048
	ds_read_b128 v[148:151], v189 offset:3072
	ds_read_b128 v[136:139], v191
	ds_read_b128 v[140:143], v191 offset:1024
	ds_read_b128 v[128:131], v191 offset:2048
	ds_read_b128 v[132:135], v191 offset:3072
	s_add_u32 s30, s28, 0xfffc0080
	s_addc_u32 s31, s29, -1
	s_cmp_eq_u32 s53, 12
	s_cselect_b32 s35, s21, s31
	s_cselect_b32 s34, s48, s30
	s_cselect_b32 s31, s19, s51
	s_cselect_b32 s30, s49, s50
	s_add_i32 m0, s27, 0xc000
	ds_read_b128 v[178:181], v192
	ds_read_b128 v[182:185], v192 offset:1024
	ds_read_b128 v[194:197], v192 offset:2048
	ds_read_b128 v[198:201], v192 offset:3072
	ds_read_b128 v[202:205], v192 offset:4096
	ds_read_b128 v[206:209], v192 offset:5120
	ds_read_b128 v[210:213], v192 offset:6144
	ds_read_b128 v[214:217], v192 offset:7168
	global_load_lds_dwordx4 v170, s[28:29]
	s_add_i32 m0, s27, 0xe000
	s_nop 0
	global_load_lds_dwordx4 v172, s[28:29]
	s_waitcnt vmcnt(8)
	s_waitcnt lgkmcnt(0)
	s_barrier
	s_setprio 1
	s_waitcnt lgkmcnt(0)
	v_mfma_scale_f32_16x16x128_f8f6f4 v[124:127], v[152:159], v[178:185], v[124:127], v254, v254 op_sel_hi:[0,0,0]
	v_mfma_scale_f32_16x16x128_f8f6f4 v[120:123], v[144:151], v[178:185], v[120:123], v254, v254 op_sel_hi:[0,0,0]
	v_mfma_scale_f32_16x16x128_f8f6f4 v[108:111], v[152:159], v[194:201], v[108:111], v254, v254 op_sel_hi:[0,0,0]
	v_mfma_scale_f32_16x16x128_f8f6f4 v[104:107], v[144:151], v[194:201], v[104:107], v254, v254 op_sel_hi:[0,0,0]
	v_mfma_scale_f32_16x16x128_f8f6f4 v[92:95], v[152:159], v[202:209], v[92:95], v254, v254 op_sel_hi:[0,0,0]
	v_mfma_scale_f32_16x16x128_f8f6f4 v[88:91], v[144:151], v[202:209], v[88:91], v254, v254 op_sel_hi:[0,0,0]
	v_mfma_scale_f32_16x16x128_f8f6f4 v[76:79], v[152:159], v[210:217], v[76:79], v254, v254 op_sel_hi:[0,0,0]
	v_mfma_scale_f32_16x16x128_f8f6f4 v[72:75], v[144:151], v[210:217], v[72:75], v254, v254 op_sel_hi:[0,0,0]
	s_setprio 0
	s_setprio 1
	v_mfma_scale_f32_16x16x128_f8f6f4 v[116:119], v[136:143], v[178:185], v[116:119], v254, v254 op_sel_hi:[0,0,0]
	v_mfma_scale_f32_16x16x128_f8f6f4 v[112:115], v[128:135], v[178:185], v[112:115], v254, v254 op_sel_hi:[0,0,0]
	v_mfma_scale_f32_16x16x128_f8f6f4 v[100:103], v[136:143], v[194:201], v[100:103], v254, v254 op_sel_hi:[0,0,0]
	v_mfma_scale_f32_16x16x128_f8f6f4 v[96:99], v[128:135], v[194:201], v[96:99], v254, v254 op_sel_hi:[0,0,0]
	v_mfma_scale_f32_16x16x128_f8f6f4 v[84:87], v[136:143], v[202:209], v[84:87], v254, v254 op_sel_hi:[0,0,0]
	v_mfma_scale_f32_16x16x128_f8f6f4 v[80:83], v[128:135], v[202:209], v[80:83], v254, v254 op_sel_hi:[0,0,0]
	v_mfma_scale_f32_16x16x128_f8f6f4 v[68:71], v[136:143], v[210:217], v[68:71], v254, v254 op_sel_hi:[0,0,0]
	v_mfma_scale_f32_16x16x128_f8f6f4 v[64:67], v[128:135], v[210:217], v[64:67], v254, v254 op_sel_hi:[0,0,0]
	s_setprio 0
	s_barrier
	s_add_i32 s56, s43, s17
	v_lshl_add_u64 v[178:179], s[30:31], 0, v[166:167]
	s_mov_b32 m0, s56
	ds_read_b128 v[194:197], v192 offset:16384
	ds_read_b128 v[198:201], v192 offset:17408
	ds_read_b128 v[202:205], v192 offset:18432
	ds_read_b128 v[206:209], v192 offset:19456
	ds_read_b128 v[210:213], v192 offset:20480
	ds_read_b128 v[214:217], v192 offset:21504
	ds_read_b128 v[218:221], v192 offset:22528
	ds_read_b128 v[222:225], v192 offset:23552
	global_load_lds_dwordx4 v[178:179], off
	s_add_i32 m0, s56, 0x2000
	s_add_u32 s56, s30, 0x40000
	v_lshl_add_u64 v[180:181], s[30:31], 0, v[162:163]
	s_addc_u32 s57, s31, 0
	s_add_i32 s58, s44, s17
	global_load_lds_dwordx4 v[180:181], off
	s_mov_b32 m0, s58
	v_lshl_add_u64 v[184:185], s[34:35], 0, v[164:165]
	global_load_lds_dwordx4 v166, s[56:57]
	s_add_i32 m0, s58, 0x2000
	s_nop 0
	global_load_lds_dwordx4 v162, s[56:57]
	v_lshl_add_u64 v[182:183], s[34:35], 0, v[168:169]
	s_mov_b32 m0, s27
	s_nop 0
	global_load_lds_dwordx4 v[182:183], off
	s_mov_b32 m0, s37
	s_nop 0
	global_load_lds_dwordx4 v[184:185], off
	s_waitcnt vmcnt(8)
	s_waitcnt lgkmcnt(0)
	s_barrier
	s_setprio 1
	s_waitcnt lgkmcnt(0)
	v_mfma_scale_f32_16x16x128_f8f6f4 v[60:63], v[152:159], v[194:201], v[60:63], v254, v254 op_sel_hi:[0,0,0]
	v_mfma_scale_f32_16x16x128_f8f6f4 v[56:59], v[144:151], v[194:201], v[56:59], v254, v254 op_sel_hi:[0,0,0]
	v_mfma_scale_f32_16x16x128_f8f6f4 v[44:47], v[152:159], v[202:209], v[44:47], v254, v254 op_sel_hi:[0,0,0]
	v_mfma_scale_f32_16x16x128_f8f6f4 v[40:43], v[144:151], v[202:209], v[40:43], v254, v254 op_sel_hi:[0,0,0]
	v_mfma_scale_f32_16x16x128_f8f6f4 v[28:31], v[152:159], v[210:217], v[28:31], v254, v254 op_sel_hi:[0,0,0]
	v_mfma_scale_f32_16x16x128_f8f6f4 v[24:27], v[144:151], v[210:217], v[24:27], v254, v254 op_sel_hi:[0,0,0]
	v_mfma_scale_f32_16x16x128_f8f6f4 v[12:15], v[152:159], v[218:225], v[12:15], v254, v254 op_sel_hi:[0,0,0]
	v_mfma_scale_f32_16x16x128_f8f6f4 v[8:11], v[144:151], v[218:225], v[8:11], v254, v254 op_sel_hi:[0,0,0]
	s_setprio 0
	s_setprio 1
	v_mfma_scale_f32_16x16x128_f8f6f4 v[52:55], v[136:143], v[194:201], v[52:55], v254, v254 op_sel_hi:[0,0,0]
	v_mfma_scale_f32_16x16x128_f8f6f4 v[48:51], v[128:135], v[194:201], v[48:51], v254, v254 op_sel_hi:[0,0,0]
	v_mfma_scale_f32_16x16x128_f8f6f4 v[36:39], v[136:143], v[202:209], v[36:39], v254, v254 op_sel_hi:[0,0,0]
	v_mfma_scale_f32_16x16x128_f8f6f4 v[32:35], v[128:135], v[202:209], v[32:35], v254, v254 op_sel_hi:[0,0,0]
	v_mfma_scale_f32_16x16x128_f8f6f4 v[20:23], v[136:143], v[210:217], v[20:23], v254, v254 op_sel_hi:[0,0,0]
	v_mfma_scale_f32_16x16x128_f8f6f4 v[16:19], v[128:135], v[210:217], v[16:19], v254, v254 op_sel_hi:[0,0,0]
	v_mfma_scale_f32_16x16x128_f8f6f4 v[4:7], v[136:143], v[218:225], v[4:7], v254, v254 op_sel_hi:[0,0,0]
	v_mfma_scale_f32_16x16x128_f8f6f4 v[0:3], v[128:135], v[218:225], v[0:3], v254, v254 op_sel_hi:[0,0,0]
	s_setprio 0
	s_barrier
; #define PG8_STAGE(bufoff, gbase, voff) do { _Pragma("unroll") for (int _i = 0; _i < 2; ++_i) \
;         __builtin_amdgcn_global_load_lds((const unsigned*)((const char*)(gbase) + (voff)[_i]), (LAS unsigned*)(lds + (bufoff) + ldsw + _i * 8192), 16, 0, 0); } while (0)
; #define PG8_LDA(dst, b, h) do { _Pragma("unroll") for (int m = 0; m < 4; ++m) _Pragma("unroll") for (int k = 0; k < 2; ++k) dst[m][k] = *(const LAS bf16x8*)(lds + PG8_SA(b, h) + aoff + m * 2048 + k * 1024); } while (0)
; #define PG8_LDB(dst, b, h) do { _Pragma("unroll") for (int n = 0; n < 2; ++n) _Pragma("unroll") for (int k = 0; k < 2; ++k) dst[n][k] = *(const LAS bf16x8*)(lds + PG8_SB(b, h) + boff + n * 2048 + k * 1024); } while (0)
; #define PG8_WAIT_V(n) asm volatile("s_waitcnt vmcnt(" #n ")" ::: "memory")
; #define PG8_WAIT_L(n) asm volatile("s_waitcnt lgkmcnt(" #n ")" ::: "memory")
; #define PG8_BAR __builtin_amdgcn_s_barrier()
; #define PG8_SCHED __builtin_amdgcn_sched_barrier(0)
; template <class Epi, class Sched, bool F8 = false>
; __device__ __forceinline__ void gemm_phase(LAS unsigned char* lds, const Gemm g, const Sched& S, const Epi& E) {
;     ...
;             PG8_LDB(B0, 1, 0); PG8_LDB(B1, 1, 1); PG8_SCHED; PG8_LDA(At, 1, 0); PG8_STAGE(PG8_SA(0, 1), a2 + hstepA, voffA);
;             PG8_WAIT_V(8); PG8_WAIT_L(0); PG8_BAR; PG8_MMA(0, 0, At, B0); PG8_MMA(0, 1, At, B1); PG8_BAR; PG8_SCHED;
;             PG8_LDA(At, 1, 1); PG8_STAGE(PG8_SB(1, 0), b3, voffB); PG8_STAGE(PG8_SB(1, 1), b3 + hstepB, voffB); PG8_STAGE(PG8_SA(1, 0), a3, voffA);
;             PG8_WAIT_V(8); PG8_WAIT_L(0); PG8_BAR; PG8_MMA(1, 0, At, B0); PG8_MMA(1, 1, At, B1); PG8_BAR; PG8_SCHED;
;         }
;         if (wr == 0) PG8_BAR;
	s_add_i32 s56, 0, 0x18000
	v_add_u32_e32 v128, s56, v187
	s_add_i32 s57, 0, 0x1c000
	ds_read_b128 v[152:155], v128
	ds_read_b128 v[156:159], v128 offset:1024
	ds_read_b128 v[144:147], v128 offset:2048
	ds_read_b128 v[148:151], v128 offset:3072
	v_add_u32_e32 v128, s57, v187
	ds_read_b128 v[136:139], v128
	ds_read_b128 v[140:143], v128 offset:1024
	ds_read_b128 v[132:135], v128 offset:3072
	ds_read_b128 v[128:131], v128 offset:2048
	s_add_u32 s34, s34, 0x40000
	s_addc_u32 s35, s35, 0
	s_mov_b32 m0, s38
	ds_read_b128 v[194:197], v192 offset:32768
	ds_read_b128 v[198:201], v192 offset:33792
	ds_read_b128 v[202:205], v192 offset:34816
	ds_read_b128 v[206:209], v192 offset:35840
	ds_read_b128 v[210:213], v192 offset:36864
	ds_read_b128 v[214:217], v192 offset:37888
	ds_read_b128 v[218:221], v192 offset:38912
	ds_read_b128 v[222:225], v192 offset:39936
	global_load_lds_dwordx4 v168, s[34:35]
	s_mov_b32 m0, s39
	s_nop 0
	global_load_lds_dwordx4 v164, s[34:35]
	s_waitcnt vmcnt(8)
	s_waitcnt lgkmcnt(0)
	s_barrier
	s_setprio 1
	s_waitcnt lgkmcnt(0)
	v_mfma_scale_f32_16x16x128_f8f6f4 v[124:127], v[152:159], v[194:201], v[124:127], v254, v254 op_sel_hi:[0,0,0]
	v_mfma_scale_f32_16x16x128_f8f6f4 v[120:123], v[144:151], v[194:201], v[120:123], v254, v254 op_sel_hi:[0,0,0]
	v_mfma_scale_f32_16x16x128_f8f6f4 v[108:111], v[152:159], v[202:209], v[108:111], v254, v254 op_sel_hi:[0,0,0]
	v_mfma_scale_f32_16x16x128_f8f6f4 v[104:107], v[144:151], v[202:209], v[104:107], v254, v254 op_sel_hi:[0,0,0]
	v_mfma_scale_f32_16x16x128_f8f6f4 v[92:95], v[152:159], v[210:217], v[92:95], v254, v254 op_sel_hi:[0,0,0]
	v_mfma_scale_f32_16x16x128_f8f6f4 v[88:91], v[144:151], v[210:217], v[88:91], v254, v254 op_sel_hi:[0,0,0]
	v_mfma_scale_f32_16x16x128_f8f6f4 v[76:79], v[152:159], v[218:225], v[76:79], v254, v254 op_sel_hi:[0,0,0]
	v_mfma_scale_f32_16x16x128_f8f6f4 v[72:75], v[144:151], v[218:225], v[72:75], v254, v254 op_sel_hi:[0,0,0]
	s_setprio 0
	s_setprio 1
	v_mfma_scale_f32_16x16x128_f8f6f4 v[116:119], v[136:143], v[194:201], v[116:119], v254, v254 op_sel_hi:[0,0,0]
	v_mfma_scale_f32_16x16x128_f8f6f4 v[112:115], v[128:135], v[194:201], v[112:115], v254, v254 op_sel_hi:[0,0,0]
	v_mfma_scale_f32_16x16x128_f8f6f4 v[100:103], v[136:143], v[202:209], v[100:103], v254, v254 op_sel_hi:[0,0,0]
	v_mfma_scale_f32_16x16x128_f8f6f4 v[96:99], v[128:135], v[202:209], v[96:99], v254, v254 op_sel_hi:[0,0,0]
	v_mfma_scale_f32_16x16x128_f8f6f4 v[84:87], v[136:143], v[210:217], v[84:87], v254, v254 op_sel_hi:[0,0,0]
	v_mfma_scale_f32_16x16x128_f8f6f4 v[80:83], v[128:135], v[210:217], v[80:83], v254, v254 op_sel_hi:[0,0,0]
	v_mfma_scale_f32_16x16x128_f8f6f4 v[68:71], v[136:143], v[218:225], v[68:71], v254, v254 op_sel_hi:[0,0,0]
	v_mfma_scale_f32_16x16x128_f8f6f4 v[64:67], v[128:135], v[218:225], v[64:67], v254, v254 op_sel_hi:[0,0,0]
	s_setprio 0
	s_barrier
	s_add_i32 s34, s56, s17
	v_lshl_add_u64 v[178:179], v[178:179], 0, s[12:13]
	s_mov_b32 m0, s34
	ds_read_b128 v[194:197], v192 offset:49152
	ds_read_b128 v[198:201], v192 offset:50176
	ds_read_b128 v[202:205], v192 offset:51200
	ds_read_b128 v[206:209], v192 offset:52224
	ds_read_b128 v[210:213], v192 offset:53248
	ds_read_b128 v[214:217], v192 offset:54272
	ds_read_b128 v[218:221], v192 offset:55296
	ds_read_b128 v[222:225], v192 offset:56320
	global_load_lds_dwordx4 v[178:179], off
	s_add_i32 m0, s34, 0x2000
	s_add_u32 s30, s30, 0x40080
	v_lshl_add_u64 v[178:179], v[180:181], 0, s[12:13]
	s_addc_u32 s31, s31, 0
	s_add_i32 s34, s57, s17
	global_load_lds_dwordx4 v[178:179], off
	s_mov_b32 m0, s34
	s_nop 0
	global_load_lds_dwordx4 v166, s[30:31]
	s_add_i32 m0, s34, 0x2000
	s_nop 0
	global_load_lds_dwordx4 v162, s[30:31]
	v_lshl_add_u64 v[178:179], v[182:183], 0, s[12:13]
	s_mov_b32 m0, s41
	s_nop 0
	global_load_lds_dwordx4 v[178:179], off
	v_lshl_add_u64 v[178:179], v[184:185], 0, s[12:13]
	s_mov_b32 m0, s42
	s_nop 0
	global_load_lds_dwordx4 v[178:179], off
	s_waitcnt vmcnt(8)
	s_waitcnt lgkmcnt(0)
	s_barrier
	s_setprio 1
	s_waitcnt lgkmcnt(0)
	v_mfma_scale_f32_16x16x128_f8f6f4 v[60:63], v[152:159], v[194:201], v[60:63], v254, v254 op_sel_hi:[0,0,0]
	v_mfma_scale_f32_16x16x128_f8f6f4 v[56:59], v[144:151], v[194:201], v[56:59], v254, v254 op_sel_hi:[0,0,0]
	v_mfma_scale_f32_16x16x128_f8f6f4 v[44:47], v[152:159], v[202:209], v[44:47], v254, v254 op_sel_hi:[0,0,0]
	v_mfma_scale_f32_16x16x128_f8f6f4 v[40:43], v[144:151], v[202:209], v[40:43], v254, v254 op_sel_hi:[0,0,0]
	v_mfma_scale_f32_16x16x128_f8f6f4 v[28:31], v[152:159], v[210:217], v[28:31], v254, v254 op_sel_hi:[0,0,0]
	v_mfma_scale_f32_16x16x128_f8f6f4 v[24:27], v[144:151], v[210:217], v[24:27], v254, v254 op_sel_hi:[0,0,0]
	v_mfma_scale_f32_16x16x128_f8f6f4 v[12:15], v[152:159], v[218:225], v[12:15], v254, v254 op_sel_hi:[0,0,0]
	v_mfma_scale_f32_16x16x128_f8f6f4 v[8:11], v[144:151], v[218:225], v[8:11], v254, v254 op_sel_hi:[0,0,0]
	s_setprio 0
	s_setprio 1
	v_mfma_scale_f32_16x16x128_f8f6f4 v[52:55], v[136:143], v[194:201], v[52:55], v254, v254 op_sel_hi:[0,0,0]
	v_mfma_scale_f32_16x16x128_f8f6f4 v[48:51], v[128:135], v[194:201], v[48:51], v254, v254 op_sel_hi:[0,0,0]
	v_mfma_scale_f32_16x16x128_f8f6f4 v[36:39], v[136:143], v[202:209], v[36:39], v254, v254 op_sel_hi:[0,0,0]
	v_mfma_scale_f32_16x16x128_f8f6f4 v[32:35], v[128:135], v[202:209], v[32:35], v254, v254 op_sel_hi:[0,0,0]
	v_mfma_scale_f32_16x16x128_f8f6f4 v[20:23], v[136:143], v[210:217], v[20:23], v254, v254 op_sel_hi:[0,0,0]
	v_mfma_scale_f32_16x16x128_f8f6f4 v[16:19], v[128:135], v[210:217], v[16:19], v254, v254 op_sel_hi:[0,0,0]
	v_mfma_scale_f32_16x16x128_f8f6f4 v[4:7], v[136:143], v[218:225], v[4:7], v254, v254 op_sel_hi:[0,0,0]
	v_mfma_scale_f32_16x16x128_f8f6f4 v[0:3], v[128:135], v[218:225], v[0:3], v254, v254 op_sel_hi:[0,0,0]
	s_setprio 0
	s_barrier
	s_add_i32 s53, s53, 2
	s_add_u32 s28, s28, 0x100
	s_addc_u32 s29, s29, 0
	s_add_u32 s50, s50, 0x100
	s_addc_u32 s51, s51, 0
	s_cmp_gt_u32 s53, 13
	s_cbranch_scc0 .LBB0_208
	s_and_b64 vcc, exec, s[14:15]
	s_cbranch_vccz .LBB0_211
	s_barrier

; #define PG8_STAGE(bufoff, gbase, voff) do { _Pragma("unroll") for (int _i = 0; _i < 2; ++_i) \
;         __builtin_amdgcn_global_load_lds((const unsigned*)((const char*)(gbase) + (voff)[_i]), (LAS unsigned*)(lds + (bufoff) + ldsw + _i * 8192), 16, 0, 0); } while (0)
; #define PG8_LDA(dst, b, h) do { _Pragma("unroll") for (int m = 0; m < 4; ++m) _Pragma("unroll") for (int k = 0; k < 2; ++k) dst[m][k] = *(const LAS bf16x8*)(lds + PG8_SA(b, h) + aoff + m * 2048 + k * 1024); } while (0)
; #define PG8_LDB(dst, b, h) do { _Pragma("unroll") for (int n = 0; n < 2; ++n) _Pragma("unroll") for (int k = 0; k < 2; ++k) dst[n][k] = *(const LAS bf16x8*)(lds + PG8_SB(b, h) + boff + n * 2048 + k * 1024); } while (0)
; #define PG8_WAIT_V(n) asm volatile("s_waitcnt vmcnt(" #n ")" ::: "memory")
; #define PG8_WAIT_L(n) asm volatile("s_waitcnt lgkmcnt(" #n ")" ::: "memory")
; #define PG8_BAR __builtin_amdgcn_s_barrier()
; #define PG8_SCHED __builtin_amdgcn_sched_barrier(0)
; template <class Epi, class Sched, bool F8 = false>
; __device__ __forceinline__ void gemm_phase(LAS unsigned char* lds, const Gemm g, const Sched& S, const Epi& E) {
;     ...
;         for (int t = 0; t < nt; t += 2) {
;             const bool last = (t == nt - 2);
;             const char* a1 = cA + (size_t)(t + 1) * kstep;
;             const char* a2 = last ? nA : cA + (size_t)(t + 2) * kstep; const char* b2 = last ? nB : cB + (size_t)(t + 2) * kstep;
;             const char* a3 = a2 + kstep; const char* b3 = b2 + kstep;
;             PG8_LDB(B0, 0, 0); PG8_LDB(B1, 0, 1); PG8_SCHED; PG8_LDA(At, 0, 0); PG8_STAGE(PG8_SA(1, 1), a1 + hstepA, voffA);
;             PG8_WAIT_V(8); PG8_WAIT_L(0); PG8_BAR; PG8_MMA(0, 0, At, B0); PG8_MMA(0, 1, At, B1); PG8_BAR; PG8_SCHED;
;             PG8_LDA(At, 0, 1); PG8_STAGE(PG8_SB(0, 0), b2, voffB); PG8_STAGE(PG8_SB(0, 1), b2 + hstepB, voffB); PG8_STAGE(PG8_SA(0, 0), a2, voffA);
;             PG8_WAIT_V(8); PG8_WAIT_L(0); PG8_BAR; PG8_MMA(1, 0, At, B0); PG8_MMA(1, 1, At, B1); PG8_BAR; PG8_SCHED;
.LBB0_356:
	ds_read_b128 v[168:171], v158
	ds_read_b128 v[172:175], v158 offset:1024
	ds_read_b128 v[176:179], v158 offset:2048
	ds_read_b128 v[180:183], v158 offset:3072
	ds_read_b128 v[184:187], v160
	ds_read_b128 v[192:195], v160 offset:1024
	ds_read_b128 v[196:199], v160 offset:2048
	ds_read_b128 v[200:203], v160 offset:3072
	s_add_u32 s8, s30, 0x100
	s_addc_u32 s9, s31, 0
	s_cmp_eq_u32 s59, 4
	s_cselect_b32 s37, s25, s9
	s_cselect_b32 s36, s24, s8
	s_cselect_b32 s35, s10, s58
	s_cselect_b32 s34, s21, s29
	s_add_i32 m0, s40, 0xc000
	ds_read_b128 v[204:207], v159
	ds_read_b128 v[208:211], v159 offset:1024
	ds_read_b128 v[212:215], v159 offset:2048
	ds_read_b128 v[216:219], v159 offset:3072
	ds_read_b128 v[220:223], v159 offset:4096
	ds_read_b128 v[224:227], v159 offset:5120
	ds_read_b128 v[228:231], v159 offset:6144
	ds_read_b128 v[232:235], v159 offset:7168
	global_load_lds_dwordx4 v144, s[30:31]
	s_add_i32 m0, s40, 0xe000
	s_nop 0
	global_load_lds_dwordx4 v146, s[30:31]
	s_waitcnt vmcnt(8)
	s_waitcnt lgkmcnt(0)
	s_barrier
	s_setprio 1
	s_waitcnt lgkmcnt(0)
	v_mfma_f32_16x16x32_bf16 v[124:127], v[168:171], v[204:207], v[124:127]
	v_mfma_f32_16x16x32_bf16 v[120:123], v[176:179], v[204:207], v[120:123]
	v_mfma_f32_16x16x32_bf16 v[108:111], v[168:171], v[212:215], v[108:111]
	v_mfma_f32_16x16x32_bf16 v[104:107], v[176:179], v[212:215], v[104:107]
	v_mfma_f32_16x16x32_bf16 v[92:95], v[168:171], v[220:223], v[92:95]
	v_mfma_f32_16x16x32_bf16 v[88:91], v[176:179], v[220:223], v[88:91]
	v_mfma_f32_16x16x32_bf16 v[76:79], v[168:171], v[228:231], v[76:79]
	v_mfma_f32_16x16x32_bf16 v[72:75], v[176:179], v[228:231], v[72:75]
	v_mfma_f32_16x16x32_bf16 v[124:127], v[172:175], v[208:211], v[124:127]
	v_mfma_f32_16x16x32_bf16 v[120:123], v[180:183], v[208:211], v[120:123]
	v_mfma_f32_16x16x32_bf16 v[108:111], v[172:175], v[216:219], v[108:111]
	v_mfma_f32_16x16x32_bf16 v[104:107], v[180:183], v[216:219], v[104:107]
	v_mfma_f32_16x16x32_bf16 v[92:95], v[172:175], v[224:227], v[92:95]
	v_mfma_f32_16x16x32_bf16 v[88:91], v[180:183], v[224:227], v[88:91]
	v_mfma_f32_16x16x32_bf16 v[76:79], v[172:175], v[232:235], v[76:79]
	v_mfma_f32_16x16x32_bf16 v[72:75], v[180:183], v[232:235], v[72:75]
	s_setprio 0
	s_setprio 1
	v_mfma_f32_16x16x32_bf16 v[116:119], v[184:187], v[204:207], v[116:119]
	v_mfma_f32_16x16x32_bf16 v[112:115], v[196:199], v[204:207], v[112:115]
	v_mfma_f32_16x16x32_bf16 v[100:103], v[184:187], v[212:215], v[100:103]
	v_mfma_f32_16x16x32_bf16 v[96:99], v[196:199], v[212:215], v[96:99]
	v_mfma_f32_16x16x32_bf16 v[84:87], v[184:187], v[220:223], v[84:87]
	v_mfma_f32_16x16x32_bf16 v[80:83], v[196:199], v[220:223], v[80:83]
	v_mfma_f32_16x16x32_bf16 v[68:71], v[184:187], v[228:231], v[68:71]
	v_mfma_f32_16x16x32_bf16 v[64:67], v[196:199], v[228:231], v[64:67]
	v_mfma_f32_16x16x32_bf16 v[116:119], v[192:195], v[208:211], v[116:119]
	v_mfma_f32_16x16x32_bf16 v[112:115], v[200:203], v[208:211], v[112:115]
	v_mfma_f32_16x16x32_bf16 v[100:103], v[192:195], v[216:219], v[100:103]
	v_mfma_f32_16x16x32_bf16 v[96:99], v[200:203], v[216:219], v[96:99]
	v_mfma_f32_16x16x32_bf16 v[84:87], v[192:195], v[224:227], v[84:87]
	v_mfma_f32_16x16x32_bf16 v[80:83], v[200:203], v[224:227], v[80:83]
	v_mfma_f32_16x16x32_bf16 v[68:71], v[192:195], v[232:235], v[68:71]
	v_mfma_f32_16x16x32_bf16 v[64:67], v[200:203], v[232:235], v[64:67]
	s_setprio 0
	s_barrier
	s_add_i32 s30, s50, s39
	v_lshl_add_u64 v[152:153], s[34:35], 0, v[130:131]
	s_mov_b32 m0, s30
	ds_read_b128 v[204:207], v159 offset:16384
	ds_read_b128 v[208:211], v159 offset:17408
	ds_read_b128 v[212:215], v159 offset:18432
	ds_read_b128 v[216:219], v159 offset:19456
	ds_read_b128 v[220:223], v159 offset:20480
	ds_read_b128 v[224:227], v159 offset:21504
	ds_read_b128 v[228:231], v159 offset:22528
	ds_read_b128 v[232:235], v159 offset:23552
	global_load_lds_dwordx4 v[152:153], off
	s_add_i32 m0, s30, 0x2000
	s_add_u32 s30, s34, 0x20000
	v_lshl_add_u64 v[188:189], s[34:35], 0, v[134:135]
	s_addc_u32 s31, s35, 0
	s_add_i32 s72, s51, s39
	global_load_lds_dwordx4 v[188:189], off
	s_mov_b32 m0, s72
	v_lshl_add_u64 v[238:239], s[36:37], 0, v[132:133]
	global_load_lds_dwordx4 v130, s[30:31]
	s_add_i32 m0, s72, 0x2000
	s_nop 0
	global_load_lds_dwordx4 v134, s[30:31]
	v_lshl_add_u64 v[236:237], s[36:37], 0, v[128:129]
	s_mov_b32 m0, s40
	s_nop 0
	global_load_lds_dwordx4 v[236:237], off
	s_mov_b32 m0, s41
	s_nop 0
	global_load_lds_dwordx4 v[238:239], off
	s_waitcnt vmcnt(8)
	s_waitcnt lgkmcnt(0)
	s_barrier
; #define PG8_STAGE(bufoff, gbase, voff) do { _Pragma("unroll") for (int _i = 0; _i < 2; ++_i) \
;         __builtin_amdgcn_global_load_lds((const unsigned*)((const char*)(gbase) + (voff)[_i]), (LAS unsigned*)(lds + (bufoff) + ldsw + _i * 8192), 16, 0, 0); } while (0)
; #define PG8_LDA(dst, b, h) do { _Pragma("unroll") for (int m = 0; m < 4; ++m) _Pragma("unroll") for (int k = 0; k < 2; ++k) dst[m][k] = *(const LAS bf16x8*)(lds + PG8_SA(b, h) + aoff + m * 2048 + k * 1024); } while (0)
; #define PG8_LDB(dst, b, h) do { _Pragma("unroll") for (int n = 0; n < 2; ++n) _Pragma("unroll") for (int k = 0; k < 2; ++k) dst[n][k] = *(const LAS bf16x8*)(lds + PG8_SB(b, h) + boff + n * 2048 + k * 1024); } while (0)
; #define PG8_WAIT_V(n) asm volatile("s_waitcnt vmcnt(" #n ")" ::: "memory")
; #define PG8_WAIT_L(n) asm volatile("s_waitcnt lgkmcnt(" #n ")" ::: "memory")
; #define PG8_BAR __builtin_amdgcn_s_barrier()
; #define PG8_SCHED __builtin_amdgcn_sched_barrier(0)
; template <class Epi, class Sched, bool F8 = false>
; __device__ __forceinline__ void gemm_phase(LAS unsigned char* lds, const Gemm g, const Sched& S, const Epi& E) {
;     ...
;             PG8_WAIT_V(8); PG8_WAIT_L(0); PG8_BAR; PG8_MMA(1, 0, At, B0); PG8_MMA(1, 1, At, B1); PG8_BAR; PG8_SCHED;
;             PG8_LDB(B0, 1, 0); PG8_LDB(B1, 1, 1); PG8_SCHED; PG8_LDA(At, 1, 0); PG8_STAGE(PG8_SA(0, 1), a2 + hstepA, voffA);
;             PG8_WAIT_V(8); PG8_WAIT_L(0); PG8_BAR; PG8_MMA(0, 0, At, B0); PG8_MMA(0, 1, At, B1); PG8_BAR; PG8_SCHED;
	s_setprio 1
	s_waitcnt lgkmcnt(0)
	v_mfma_f32_16x16x32_bf16 v[60:63], v[168:171], v[204:207], v[60:63]
	v_mfma_f32_16x16x32_bf16 v[56:59], v[176:179], v[204:207], v[56:59]
	v_mfma_f32_16x16x32_bf16 v[44:47], v[168:171], v[212:215], v[44:47]
	v_mfma_f32_16x16x32_bf16 v[40:43], v[176:179], v[212:215], v[40:43]
	v_mfma_f32_16x16x32_bf16 v[28:31], v[168:171], v[220:223], v[28:31]
	v_mfma_f32_16x16x32_bf16 v[24:27], v[176:179], v[220:223], v[24:27]
	v_mfma_f32_16x16x32_bf16 v[12:15], v[168:171], v[228:231], v[12:15]
	v_mfma_f32_16x16x32_bf16 v[8:11], v[176:179], v[228:231], v[8:11]
	v_mfma_f32_16x16x32_bf16 v[60:63], v[172:175], v[208:211], v[60:63]
	v_mfma_f32_16x16x32_bf16 v[56:59], v[180:183], v[208:211], v[56:59]
	v_mfma_f32_16x16x32_bf16 v[44:47], v[172:175], v[216:219], v[44:47]
	v_mfma_f32_16x16x32_bf16 v[40:43], v[180:183], v[216:219], v[40:43]
	v_mfma_f32_16x16x32_bf16 v[28:31], v[172:175], v[224:227], v[28:31]
	v_mfma_f32_16x16x32_bf16 v[24:27], v[180:183], v[224:227], v[24:27]
	v_mfma_f32_16x16x32_bf16 v[12:15], v[172:175], v[232:235], v[12:15]
	v_mfma_f32_16x16x32_bf16 v[8:11], v[180:183], v[232:235], v[8:11]
	s_setprio 0
	s_setprio 1
	v_mfma_f32_16x16x32_bf16 v[52:55], v[184:187], v[204:207], v[52:55]
	v_mfma_f32_16x16x32_bf16 v[48:51], v[196:199], v[204:207], v[48:51]
	v_mfma_f32_16x16x32_bf16 v[36:39], v[184:187], v[212:215], v[36:39]
	v_mfma_f32_16x16x32_bf16 v[32:35], v[196:199], v[212:215], v[32:35]
	v_mfma_f32_16x16x32_bf16 v[20:23], v[184:187], v[220:223], v[20:23]
	v_mfma_f32_16x16x32_bf16 v[16:19], v[196:199], v[220:223], v[16:19]
	v_mfma_f32_16x16x32_bf16 v[4:7], v[184:187], v[228:231], v[4:7]
	v_mfma_f32_16x16x32_bf16 v[0:3], v[196:199], v[228:231], v[0:3]
	v_mfma_f32_16x16x32_bf16 v[52:55], v[192:195], v[208:211], v[52:55]
	v_mfma_f32_16x16x32_bf16 v[48:51], v[200:203], v[208:211], v[48:51]
	v_mfma_f32_16x16x32_bf16 v[36:39], v[192:195], v[216:219], v[36:39]
	v_mfma_f32_16x16x32_bf16 v[32:35], v[200:203], v[216:219], v[32:35]
	v_mfma_f32_16x16x32_bf16 v[20:23], v[192:195], v[224:227], v[20:23]
	v_mfma_f32_16x16x32_bf16 v[16:19], v[200:203], v[224:227], v[16:19]
	v_mfma_f32_16x16x32_bf16 v[4:7], v[192:195], v[232:235], v[4:7]
	v_mfma_f32_16x16x32_bf16 v[0:3], v[200:203], v[232:235], v[0:3]
	s_setprio 0
	s_barrier
	s_add_i32 s72, 0, 0x18000
	v_add_u32_e32 v154, s72, v156
	s_add_i32 s73, 0, 0x1c000
	ds_read_b128 v[168:171], v154
	ds_read_b128 v[172:175], v154 offset:1024
	ds_read_b128 v[176:179], v154 offset:2048
	ds_read_b128 v[180:183], v154 offset:3072
	v_add_u32_e32 v154, s73, v156
	ds_read_b128 v[184:187], v154
	ds_read_b128 v[192:195], v154 offset:1024
	ds_read_b128 v[196:199], v154 offset:2048
	ds_read_b128 v[200:203], v154 offset:3072
	s_add_u32 s30, s36, 0xc0000
	s_addc_u32 s31, s37, 0
	s_mov_b32 m0, s42
	ds_read_b128 v[204:207], v159 offset:32768
	ds_read_b128 v[208:211], v159 offset:33792
	ds_read_b128 v[212:215], v159 offset:34816
	ds_read_b128 v[216:219], v159 offset:35840
	ds_read_b128 v[220:223], v159 offset:36864
	ds_read_b128 v[224:227], v159 offset:37888
	ds_read_b128 v[228:231], v159 offset:38912
	ds_read_b128 v[232:235], v159 offset:39936
	global_load_lds_dwordx4 v128, s[30:31]
	s_mov_b32 m0, s43
	s_nop 0
	global_load_lds_dwordx4 v132, s[30:31]
	s_waitcnt vmcnt(8)
	s_waitcnt lgkmcnt(0)
	s_barrier
	s_setprio 1
	s_waitcnt lgkmcnt(0)
	v_mfma_f32_16x16x32_bf16 v[124:127], v[168:171], v[204:207], v[124:127]
	v_mfma_f32_16x16x32_bf16 v[120:123], v[176:179], v[204:207], v[120:123]
	v_mfma_f32_16x16x32_bf16 v[108:111], v[168:171], v[212:215], v[108:111]
	v_mfma_f32_16x16x32_bf16 v[104:107], v[176:179], v[212:215], v[104:107]
	v_mfma_f32_16x16x32_bf16 v[92:95], v[168:171], v[220:223], v[92:95]
	v_mfma_f32_16x16x32_bf16 v[88:91], v[176:179], v[220:223], v[88:91]
	v_mfma_f32_16x16x32_bf16 v[76:79], v[168:171], v[228:231], v[76:79]
	v_mfma_f32_16x16x32_bf16 v[72:75], v[176:179], v[228:231], v[72:75]
	v_mfma_f32_16x16x32_bf16 v[124:127], v[172:175], v[208:211], v[124:127]
	v_mfma_f32_16x16x32_bf16 v[120:123], v[180:183], v[208:211], v[120:123]
	v_mfma_f32_16x16x32_bf16 v[108:111], v[172:175], v[216:219], v[108:111]
	v_mfma_f32_16x16x32_bf16 v[104:107], v[180:183], v[216:219], v[104:107]
	v_mfma_f32_16x16x32_bf16 v[92:95], v[172:175], v[224:227], v[92:95]
	v_mfma_f32_16x16x32_bf16 v[88:91], v[180:183], v[224:227], v[88:91]
	v_mfma_f32_16x16x32_bf16 v[76:79], v[172:175], v[232:235], v[76:79]
	v_mfma_f32_16x16x32_bf16 v[72:75], v[180:183], v[232:235], v[72:75]
	s_setprio 0
	s_setprio 1
	v_mfma_f32_16x16x32_bf16 v[116:119], v[184:187], v[204:207], v[116:119]
	v_mfma_f32_16x16x32_bf16 v[112:115], v[196:199], v[204:207], v[112:115]
	v_mfma_f32_16x16x32_bf16 v[100:103], v[184:187], v[212:215], v[100:103]
	v_mfma_f32_16x16x32_bf16 v[96:99], v[196:199], v[212:215], v[96:99]
	v_mfma_f32_16x16x32_bf16 v[84:87], v[184:187], v[220:223], v[84:87]
	v_mfma_f32_16x16x32_bf16 v[80:83], v[196:199], v[220:223], v[80:83]
	v_mfma_f32_16x16x32_bf16 v[68:71], v[184:187], v[228:231], v[68:71]
	v_mfma_f32_16x16x32_bf16 v[64:67], v[196:199], v[228:231], v[64:67]
	v_mfma_f32_16x16x32_bf16 v[116:119], v[192:195], v[208:211], v[116:119]
	v_mfma_f32_16x16x32_bf16 v[112:115], v[200:203], v[208:211], v[112:115]
	v_mfma_f32_16x16x32_bf16 v[100:103], v[192:195], v[216:219], v[100:103]
	v_mfma_f32_16x16x32_bf16 v[96:99], v[200:203], v[216:219], v[96:99]
	v_mfma_f32_16x16x32_bf16 v[84:87], v[192:195], v[224:227], v[84:87]
	v_mfma_f32_16x16x32_bf16 v[80:83], v[200:203], v[224:227], v[80:83]
	v_mfma_f32_16x16x32_bf16 v[68:71], v[192:195], v[232:235], v[68:71]
	v_mfma_f32_16x16x32_bf16 v[64:67], v[200:203], v[232:235], v[64:67]
	s_setprio 0
	s_barrier
; #define PG8_STAGE(bufoff, gbase, voff) do { _Pragma("unroll") for (int _i = 0; _i < 2; ++_i) \
;         __builtin_amdgcn_global_load_lds((const unsigned*)((const char*)(gbase) + (voff)[_i]), (LAS unsigned*)(lds + (bufoff) + ldsw + _i * 8192), 16, 0, 0); } while (0)
; #define PG8_LDA(dst, b, h) do { _Pragma("unroll") for (int m = 0; m < 4; ++m) _Pragma("unroll") for (int k = 0; k < 2; ++k) dst[m][k] = *(const LAS bf16x8*)(lds + PG8_SA(b, h) + aoff + m * 2048 + k * 1024); } while (0)
; #define PG8_WAIT_V(n) asm volatile("s_waitcnt vmcnt(" #n ")" ::: "memory")
; #define PG8_WAIT_L(n) asm volatile("s_waitcnt lgkmcnt(" #n ")" ::: "memory")
; #define PG8_BAR __builtin_amdgcn_s_barrier()
; #define PG8_SCHED __builtin_amdgcn_sched_barrier(0)
; template <class Epi, class Sched, bool F8 = false>
; __device__ __forceinline__ void gemm_phase(LAS unsigned char* lds, const Gemm g, const Sched& S, const Epi& E) {
;     ...
;             PG8_LDA(At, 1, 1); PG8_STAGE(PG8_SB(1, 0), b3, voffB); PG8_STAGE(PG8_SB(1, 1), b3 + hstepB, voffB); PG8_STAGE(PG8_SA(1, 0), a3, voffA);
;             PG8_WAIT_V(8); PG8_WAIT_L(0); PG8_BAR; PG8_MMA(1, 0, At, B0); PG8_MMA(1, 1, At, B1); PG8_BAR; PG8_SCHED;
;         }
;         if (wr == 0) PG8_BAR;
	s_add_i32 s30, s72, s39
	v_lshl_add_u64 v[152:153], v[152:153], 0, s[16:17]
	s_mov_b32 m0, s30
	ds_read_b128 v[204:207], v159 offset:49152
	ds_read_b128 v[208:211], v159 offset:50176
	ds_read_b128 v[212:215], v159 offset:51200
	ds_read_b128 v[216:219], v159 offset:52224
	ds_read_b128 v[220:223], v159 offset:53248
	ds_read_b128 v[224:227], v159 offset:54272
	ds_read_b128 v[228:231], v159 offset:55296
	ds_read_b128 v[232:235], v159 offset:56320
	global_load_lds_dwordx4 v[152:153], off
	s_add_i32 m0, s30, 0x2000
	s_add_u32 s30, s34, 0x20080
	v_lshl_add_u64 v[152:153], v[188:189], 0, s[16:17]
	s_addc_u32 s31, s35, 0
	s_add_i32 s34, s73, s39
	global_load_lds_dwordx4 v[152:153], off
	s_mov_b32 m0, s34
	s_nop 0
	global_load_lds_dwordx4 v130, s[30:31]
	s_add_i32 m0, s34, 0x2000
	s_nop 0
	global_load_lds_dwordx4 v134, s[30:31]
	v_lshl_add_u64 v[152:153], v[236:237], 0, s[16:17]
	s_mov_b32 m0, s45
	s_nop 0
	global_load_lds_dwordx4 v[152:153], off
	v_lshl_add_u64 v[152:153], v[238:239], 0, s[16:17]
	s_mov_b32 m0, s47
	s_nop 0
	global_load_lds_dwordx4 v[152:153], off
	s_waitcnt vmcnt(8)
	s_waitcnt lgkmcnt(0)
	s_barrier
	s_setprio 1
	s_waitcnt lgkmcnt(0)
	v_mfma_f32_16x16x32_bf16 v[60:63], v[168:171], v[204:207], v[60:63]
	v_mfma_f32_16x16x32_bf16 v[56:59], v[176:179], v[204:207], v[56:59]
	v_mfma_f32_16x16x32_bf16 v[44:47], v[168:171], v[212:215], v[44:47]
	v_mfma_f32_16x16x32_bf16 v[40:43], v[176:179], v[212:215], v[40:43]
	v_mfma_f32_16x16x32_bf16 v[28:31], v[168:171], v[220:223], v[28:31]
	v_mfma_f32_16x16x32_bf16 v[24:27], v[176:179], v[220:223], v[24:27]
	v_mfma_f32_16x16x32_bf16 v[12:15], v[168:171], v[228:231], v[12:15]
	v_mfma_f32_16x16x32_bf16 v[8:11], v[176:179], v[228:231], v[8:11]
	v_mfma_f32_16x16x32_bf16 v[60:63], v[172:175], v[208:211], v[60:63]
	v_mfma_f32_16x16x32_bf16 v[56:59], v[180:183], v[208:211], v[56:59]
	v_mfma_f32_16x16x32_bf16 v[44:47], v[172:175], v[216:219], v[44:47]
	v_mfma_f32_16x16x32_bf16 v[40:43], v[180:183], v[216:219], v[40:43]
	v_mfma_f32_16x16x32_bf16 v[28:31], v[172:175], v[224:227], v[28:31]
	v_mfma_f32_16x16x32_bf16 v[24:27], v[180:183], v[224:227], v[24:27]
	v_mfma_f32_16x16x32_bf16 v[12:15], v[172:175], v[232:235], v[12:15]
	v_mfma_f32_16x16x32_bf16 v[8:11], v[180:183], v[232:235], v[8:11]
	s_setprio 0
	s_setprio 1
	v_mfma_f32_16x16x32_bf16 v[52:55], v[184:187], v[204:207], v[52:55]
	v_mfma_f32_16x16x32_bf16 v[48:51], v[196:199], v[204:207], v[48:51]
	v_mfma_f32_16x16x32_bf16 v[36:39], v[184:187], v[212:215], v[36:39]
	v_mfma_f32_16x16x32_bf16 v[32:35], v[196:199], v[212:215], v[32:35]
	v_mfma_f32_16x16x32_bf16 v[20:23], v[184:187], v[220:223], v[20:23]
	v_mfma_f32_16x16x32_bf16 v[16:19], v[196:199], v[220:223], v[16:19]
	v_mfma_f32_16x16x32_bf16 v[4:7], v[184:187], v[228:231], v[4:7]
	v_mfma_f32_16x16x32_bf16 v[0:3], v[196:199], v[228:231], v[0:3]
	v_mfma_f32_16x16x32_bf16 v[52:55], v[192:195], v[208:211], v[52:55]
	v_mfma_f32_16x16x32_bf16 v[48:51], v[200:203], v[208:211], v[48:51]
	v_mfma_f32_16x16x32_bf16 v[36:39], v[192:195], v[216:219], v[36:39]
	v_mfma_f32_16x16x32_bf16 v[32:35], v[200:203], v[216:219], v[32:35]
	v_mfma_f32_16x16x32_bf16 v[20:23], v[192:195], v[224:227], v[20:23]
	v_mfma_f32_16x16x32_bf16 v[16:19], v[200:203], v[224:227], v[16:19]
	v_mfma_f32_16x16x32_bf16 v[4:7], v[192:195], v[232:235], v[4:7]
	v_mfma_f32_16x16x32_bf16 v[0:3], v[200:203], v[232:235], v[0:3]
	s_setprio 0
	s_barrier
	s_add_i32 s59, s59, 2
	s_add_u32 s29, s29, 0x100
	s_addc_u32 s58, s58, 0
	s_cmp_gt_u32 s59, 5
	s_mov_b64 s[30:31], s[8:9]
	s_cbranch_scc0 .LBB0_356
	s_and_b64 vcc, exec, s[18:19]
	s_cbranch_vccz .LBB0_359
	s_barrier

; #define PG8_STAGE(bufoff, gbase, voff) do { _Pragma("unroll") for (int _i = 0; _i < 2; ++_i) \
;         __builtin_amdgcn_global_load_lds((const unsigned*)((const char*)(gbase) + (voff)[_i]), (LAS unsigned*)(lds + (bufoff) + ldsw + _i * 8192), 16, 0, 0); } while (0)
; #define PG8_LDA(dst, b, h) do { _Pragma("unroll") for (int m = 0; m < 4; ++m) _Pragma("unroll") for (int k = 0; k < 2; ++k) dst[m][k] = *(const LAS bf16x8*)(lds + PG8_SA(b, h) + aoff + m * 2048 + k * 1024); } while (0)
; #define PG8_LDB(dst, b, h) do { _Pragma("unroll") for (int n = 0; n < 2; ++n) _Pragma("unroll") for (int k = 0; k < 2; ++k) dst[n][k] = *(const LAS bf16x8*)(lds + PG8_SB(b, h) + boff + n * 2048 + k * 1024); } while (0)
; #define PG8_WAIT_V(n) asm volatile("s_waitcnt vmcnt(" #n ")" ::: "memory")
; #define PG8_WAIT_L(n) asm volatile("s_waitcnt lgkmcnt(" #n ")" ::: "memory")
; #define PG8_BAR __builtin_amdgcn_s_barrier()
; #define PG8_SCHED __builtin_amdgcn_sched_barrier(0)
; template <class Epi, class Sched, bool F8 = false>
; __device__ __forceinline__ void gemm_phase(LAS unsigned char* lds, const Gemm g, const Sched& S, const Epi& E) {
;     ...
;         const char* nA = has_next ? (const char*)g.A + (size_t)nxt.pm * tstepA + nxt.aoff : cA; const char* nB = has_next ? (const char*)g.Bt + (size_t)nxt.pn * tstepB + nxt.boff : cB;
;         const int nt = cur.nt ? cur.nt : K / BK;
;         for (int t = 0; t < nt; t += 2) {
;             const bool last = (t == nt - 2);
;             const char* a1 = cA + (size_t)(t + 1) * kstep;
;             const char* a2 = last ? nA : cA + (size_t)(t + 2) * kstep; const char* b2 = last ? nB : cB + (size_t)(t + 2) * kstep;
;             const char* a3 = a2 + kstep; const char* b3 = b2 + kstep;
;             PG8_LDB(B0, 0, 0); PG8_LDB(B1, 0, 1); PG8_SCHED; PG8_LDA(At, 0, 0); PG8_STAGE(PG8_SA(1, 1), a1 + hstepA, voffA);
;             PG8_WAIT_V(8); PG8_WAIT_L(0); PG8_BAR; PG8_MMA(0, 0, At, B0); PG8_MMA(0, 1, At, B1); PG8_BAR; PG8_SCHED;
;             PG8_LDA(At, 0, 1); PG8_STAGE(PG8_SB(0, 0), b2, voffB); PG8_STAGE(PG8_SB(0, 1), b2 + hstepB, voffB); PG8_STAGE(PG8_SA(0, 0), a2, voffA);
;             PG8_WAIT_V(8); PG8_WAIT_L(0); PG8_BAR; PG8_MMA(1, 0, At, B0); PG8_MMA(1, 1, At, B1); PG8_BAR; PG8_SCHED;
.LBB0_753:
	v_add_u32_e32 v140, s48, v197
	v_add_u32_e32 v156, s91, v197
	ds_read_b128 v[128:131], v140
	ds_read_b128 v[132:135], v140 offset:1024
	ds_read_b128 v[136:139], v140 offset:2048
	ds_read_b128 v[140:143], v140 offset:3072
	ds_read_b128 v[144:147], v156
	ds_read_b128 v[148:151], v156 offset:1024
	ds_read_b128 v[152:155], v156 offset:2048
	ds_read_b128 v[156:159], v156 offset:3072
	s_add_i32 s80, s34, 2
	s_add_u32 s35, s30, 0xfff80080
	s_addc_u32 s36, s31, -1
	s_cmp_eq_u32 s77, s34
	s_cselect_b32 s34, s76, s78
	s_cselect_b32 s37, s25, s36
	s_cselect_b32 s36, s75, s35
	s_cselect_b32 s35, s21, s79
	s_add_i32 m0, s40, 0xc000
	ds_read_b128 v[160:163], v199
	ds_read_b128 v[164:167], v199 offset:1024
	ds_read_b128 v[168:171], v199 offset:2048
	ds_read_b128 v[172:175], v199 offset:3072
	ds_read_b128 v[200:203], v199 offset:4096
	ds_read_b128 v[204:207], v199 offset:5120
	ds_read_b128 v[208:211], v199 offset:6144
	ds_read_b128 v[212:215], v199 offset:7168
	global_load_lds_dwordx4 v186, s[30:31]
	s_add_i32 m0, s40, 0xe000
	s_nop 0
	global_load_lds_dwordx4 v188, s[30:31]
	s_waitcnt vmcnt(8)
	s_waitcnt lgkmcnt(0)
	s_barrier
	s_setprio 1
	s_waitcnt lgkmcnt(0)
	v_mfma_f32_16x16x32_bf16 v[124:127], v[128:131], v[160:163], v[124:127]
	v_mfma_f32_16x16x32_bf16 v[120:123], v[136:139], v[160:163], v[120:123]
	v_mfma_f32_16x16x32_bf16 v[116:119], v[128:131], v[168:171], v[116:119]
	v_mfma_f32_16x16x32_bf16 v[112:115], v[136:139], v[168:171], v[112:115]
	v_mfma_f32_16x16x32_bf16 v[108:111], v[128:131], v[200:203], v[108:111]
	v_mfma_f32_16x16x32_bf16 v[104:107], v[136:139], v[200:203], v[104:107]
	v_mfma_f32_16x16x32_bf16 v[100:103], v[128:131], v[208:211], v[100:103]
	v_mfma_f32_16x16x32_bf16 v[96:99], v[136:139], v[208:211], v[96:99]
	v_mfma_f32_16x16x32_bf16 v[124:127], v[132:135], v[164:167], v[124:127]
	v_mfma_f32_16x16x32_bf16 v[120:123], v[140:143], v[164:167], v[120:123]
	v_mfma_f32_16x16x32_bf16 v[116:119], v[132:135], v[172:175], v[116:119]
	v_mfma_f32_16x16x32_bf16 v[112:115], v[140:143], v[172:175], v[112:115]
	v_mfma_f32_16x16x32_bf16 v[108:111], v[132:135], v[204:207], v[108:111]
	v_mfma_f32_16x16x32_bf16 v[104:107], v[140:143], v[204:207], v[104:107]
	v_mfma_f32_16x16x32_bf16 v[100:103], v[132:135], v[212:215], v[100:103]
	v_mfma_f32_16x16x32_bf16 v[96:99], v[140:143], v[212:215], v[96:99]
	s_setprio 0
	s_setprio 1
	v_mfma_f32_16x16x32_bf16 v[92:95], v[144:147], v[160:163], v[92:95]
	v_mfma_f32_16x16x32_bf16 v[88:91], v[152:155], v[160:163], v[88:91]
	v_mfma_f32_16x16x32_bf16 v[84:87], v[144:147], v[168:171], v[84:87]
	v_mfma_f32_16x16x32_bf16 v[80:83], v[152:155], v[168:171], v[80:83]
	v_mfma_f32_16x16x32_bf16 v[76:79], v[144:147], v[200:203], v[76:79]
	v_mfma_f32_16x16x32_bf16 v[72:75], v[152:155], v[200:203], v[72:75]
	v_mfma_f32_16x16x32_bf16 v[68:71], v[144:147], v[208:211], v[68:71]
	v_mfma_f32_16x16x32_bf16 v[64:67], v[152:155], v[208:211], v[64:67]
	v_mfma_f32_16x16x32_bf16 v[92:95], v[148:151], v[164:167], v[92:95]
	v_mfma_f32_16x16x32_bf16 v[88:91], v[156:159], v[164:167], v[88:91]
	v_mfma_f32_16x16x32_bf16 v[84:87], v[148:151], v[172:175], v[84:87]
	v_mfma_f32_16x16x32_bf16 v[80:83], v[156:159], v[172:175], v[80:83]
	v_mfma_f32_16x16x32_bf16 v[76:79], v[148:151], v[204:207], v[76:79]
	v_mfma_f32_16x16x32_bf16 v[72:75], v[156:159], v[204:207], v[72:75]
	v_mfma_f32_16x16x32_bf16 v[68:71], v[148:151], v[212:215], v[68:71]
	v_mfma_f32_16x16x32_bf16 v[64:67], v[156:159], v[212:215], v[64:67]
	s_setprio 0
	s_barrier
	s_add_i32 s81, s48, s38
	v_lshl_add_u64 v[216:217], s[34:35], 0, v[180:181]
	s_mov_b32 m0, s81
	ds_read_b128 v[160:163], v199 offset:16384
	ds_read_b128 v[164:167], v199 offset:17408
	ds_read_b128 v[168:171], v199 offset:18432
	ds_read_b128 v[172:175], v199 offset:19456
	ds_read_b128 v[200:203], v199 offset:20480
	ds_read_b128 v[204:207], v199 offset:21504
	ds_read_b128 v[208:211], v199 offset:22528
	ds_read_b128 v[212:215], v199 offset:23552
	global_load_lds_dwordx4 v[216:217], off
	s_add_i32 m0, s81, 0x2000
	s_add_u32 s82, s34, 0x80000
	v_lshl_add_u64 v[218:219], s[34:35], 0, v[176:177]
	s_addc_u32 s83, s35, 0
	s_add_i32 s81, s91, s38
	global_load_lds_dwordx4 v[218:219], off
	s_mov_b32 m0, s81
	v_lshl_add_u64 v[222:223], s[36:37], 0, v[178:179]
	global_load_lds_dwordx4 v180, s[82:83]
	s_add_i32 m0, s81, 0x2000
	s_nop 0
	global_load_lds_dwordx4 v176, s[82:83]
	v_lshl_add_u64 v[220:221], s[36:37], 0, v[182:183]
	s_mov_b32 m0, s40
	s_nop 0
	global_load_lds_dwordx4 v[220:221], off
	s_mov_b32 m0, s41
	s_nop 0
	global_load_lds_dwordx4 v[222:223], off
	s_waitcnt vmcnt(8)
	s_waitcnt lgkmcnt(0)
	s_barrier
; #define PG8_STAGE(bufoff, gbase, voff) do { _Pragma("unroll") for (int _i = 0; _i < 2; ++_i) \
;         __builtin_amdgcn_global_load_lds((const unsigned*)((const char*)(gbase) + (voff)[_i]), (LAS unsigned*)(lds + (bufoff) + ldsw + _i * 8192), 16, 0, 0); } while (0)
; #define PG8_LDA(dst, b, h) do { _Pragma("unroll") for (int m = 0; m < 4; ++m) _Pragma("unroll") for (int k = 0; k < 2; ++k) dst[m][k] = *(const LAS bf16x8*)(lds + PG8_SA(b, h) + aoff + m * 2048 + k * 1024); } while (0)
; #define PG8_LDB(dst, b, h) do { _Pragma("unroll") for (int n = 0; n < 2; ++n) _Pragma("unroll") for (int k = 0; k < 2; ++k) dst[n][k] = *(const LAS bf16x8*)(lds + PG8_SB(b, h) + boff + n * 2048 + k * 1024); } while (0)
; #define PG8_WAIT_V(n) asm volatile("s_waitcnt vmcnt(" #n ")" ::: "memory")
; #define PG8_WAIT_L(n) asm volatile("s_waitcnt lgkmcnt(" #n ")" ::: "memory")
; #define PG8_BAR __builtin_amdgcn_s_barrier()
; #define PG8_SCHED __builtin_amdgcn_sched_barrier(0)
; template <class Epi, class Sched, bool F8 = false>
; __device__ __forceinline__ void gemm_phase(LAS unsigned char* lds, const Gemm g, const Sched& S, const Epi& E) {
;     ...
;             PG8_WAIT_V(8); PG8_WAIT_L(0); PG8_BAR; PG8_MMA(1, 0, At, B0); PG8_MMA(1, 1, At, B1); PG8_BAR; PG8_SCHED;
;             PG8_LDB(B0, 1, 0); PG8_LDB(B1, 1, 1); PG8_SCHED; PG8_LDA(At, 1, 0); PG8_STAGE(PG8_SA(0, 1), a2 + hstepA, voffA);
;             PG8_WAIT_V(8); PG8_WAIT_L(0); PG8_BAR; PG8_MMA(0, 0, At, B0); PG8_MMA(0, 1, At, B1); PG8_BAR; PG8_SCHED;
	s_setprio 1
	s_waitcnt lgkmcnt(0)
	v_mfma_f32_16x16x32_bf16 v[60:63], v[128:131], v[160:163], v[60:63]
	v_mfma_f32_16x16x32_bf16 v[56:59], v[136:139], v[160:163], v[56:59]
	v_mfma_f32_16x16x32_bf16 v[52:55], v[128:131], v[168:171], v[52:55]
	v_mfma_f32_16x16x32_bf16 v[48:51], v[136:139], v[168:171], v[48:51]
	v_mfma_f32_16x16x32_bf16 v[44:47], v[128:131], v[200:203], v[44:47]
	v_mfma_f32_16x16x32_bf16 v[40:43], v[136:139], v[200:203], v[40:43]
	v_mfma_f32_16x16x32_bf16 v[36:39], v[128:131], v[208:211], v[36:39]
	v_mfma_f32_16x16x32_bf16 v[32:35], v[136:139], v[208:211], v[32:35]
	v_mfma_f32_16x16x32_bf16 v[60:63], v[132:135], v[164:167], v[60:63]
	v_mfma_f32_16x16x32_bf16 v[56:59], v[140:143], v[164:167], v[56:59]
	v_mfma_f32_16x16x32_bf16 v[52:55], v[132:135], v[172:175], v[52:55]
	v_mfma_f32_16x16x32_bf16 v[48:51], v[140:143], v[172:175], v[48:51]
	v_mfma_f32_16x16x32_bf16 v[44:47], v[132:135], v[204:207], v[44:47]
	v_mfma_f32_16x16x32_bf16 v[40:43], v[140:143], v[204:207], v[40:43]
	v_mfma_f32_16x16x32_bf16 v[36:39], v[132:135], v[212:215], v[36:39]
	v_mfma_f32_16x16x32_bf16 v[32:35], v[140:143], v[212:215], v[32:35]
	s_setprio 0
	s_setprio 1
	v_mfma_f32_16x16x32_bf16 v[28:31], v[144:147], v[160:163], v[28:31]
	v_mfma_f32_16x16x32_bf16 v[24:27], v[152:155], v[160:163], v[24:27]
	v_mfma_f32_16x16x32_bf16 v[20:23], v[144:147], v[168:171], v[20:23]
	v_mfma_f32_16x16x32_bf16 v[16:19], v[152:155], v[168:171], v[16:19]
	v_mfma_f32_16x16x32_bf16 v[12:15], v[144:147], v[200:203], v[12:15]
	v_mfma_f32_16x16x32_bf16 v[8:11], v[152:155], v[200:203], v[8:11]
	v_mfma_f32_16x16x32_bf16 v[4:7], v[144:147], v[208:211], v[4:7]
	v_mfma_f32_16x16x32_bf16 v[0:3], v[152:155], v[208:211], v[0:3]
	v_mfma_f32_16x16x32_bf16 v[28:31], v[148:151], v[164:167], v[28:31]
	v_mfma_f32_16x16x32_bf16 v[24:27], v[156:159], v[164:167], v[24:27]
	v_mfma_f32_16x16x32_bf16 v[20:23], v[148:151], v[172:175], v[20:23]
	v_mfma_f32_16x16x32_bf16 v[16:19], v[156:159], v[172:175], v[16:19]
	v_mfma_f32_16x16x32_bf16 v[12:15], v[148:151], v[204:207], v[12:15]
	v_mfma_f32_16x16x32_bf16 v[8:11], v[156:159], v[204:207], v[8:11]
	v_mfma_f32_16x16x32_bf16 v[4:7], v[148:151], v[212:215], v[4:7]
	v_mfma_f32_16x16x32_bf16 v[0:3], v[156:159], v[212:215], v[0:3]
	s_setprio 0
	s_barrier
	s_add_i32 s81, 0, 0x18000
	s_add_i32 s82, 0, 0x1c000
	v_add_u32_e32 v140, s81, v197
	v_add_u32_e32 v156, s82, v197
	ds_read_b128 v[128:131], v140
	ds_read_b128 v[132:135], v140 offset:1024
	ds_read_b128 v[136:139], v140 offset:2048
	ds_read_b128 v[140:143], v140 offset:3072
	ds_read_b128 v[144:147], v156
	ds_read_b128 v[148:151], v156 offset:1024
	ds_read_b128 v[152:155], v156 offset:2048
	ds_read_b128 v[156:159], v156 offset:3072
	s_add_u32 s36, s36, 0x80000
	s_addc_u32 s37, s37, 0
	s_mov_b32 m0, s42
	ds_read_b128 v[160:163], v199 offset:32768
	ds_read_b128 v[164:167], v199 offset:33792
	ds_read_b128 v[168:171], v199 offset:34816
	ds_read_b128 v[172:175], v199 offset:35840
	ds_read_b128 v[200:203], v199 offset:36864
	ds_read_b128 v[204:207], v199 offset:37888
	ds_read_b128 v[208:211], v199 offset:38912
	ds_read_b128 v[212:215], v199 offset:39936
	global_load_lds_dwordx4 v182, s[36:37]
	s_mov_b32 m0, s43
	s_nop 0
	global_load_lds_dwordx4 v178, s[36:37]
	s_waitcnt vmcnt(8)
	s_waitcnt lgkmcnt(0)
	s_barrier
	s_setprio 1
	s_waitcnt lgkmcnt(0)
	v_mfma_f32_16x16x32_bf16 v[124:127], v[128:131], v[160:163], v[124:127]
	v_mfma_f32_16x16x32_bf16 v[120:123], v[136:139], v[160:163], v[120:123]
	v_mfma_f32_16x16x32_bf16 v[116:119], v[128:131], v[168:171], v[116:119]
	v_mfma_f32_16x16x32_bf16 v[112:115], v[136:139], v[168:171], v[112:115]
	v_mfma_f32_16x16x32_bf16 v[108:111], v[128:131], v[200:203], v[108:111]
	v_mfma_f32_16x16x32_bf16 v[104:107], v[136:139], v[200:203], v[104:107]
	v_mfma_f32_16x16x32_bf16 v[100:103], v[128:131], v[208:211], v[100:103]
	v_mfma_f32_16x16x32_bf16 v[96:99], v[136:139], v[208:211], v[96:99]
	v_mfma_f32_16x16x32_bf16 v[124:127], v[132:135], v[164:167], v[124:127]
	v_mfma_f32_16x16x32_bf16 v[120:123], v[140:143], v[164:167], v[120:123]
	v_mfma_f32_16x16x32_bf16 v[116:119], v[132:135], v[172:175], v[116:119]
	v_mfma_f32_16x16x32_bf16 v[112:115], v[140:143], v[172:175], v[112:115]
	v_mfma_f32_16x16x32_bf16 v[108:111], v[132:135], v[204:207], v[108:111]
	v_mfma_f32_16x16x32_bf16 v[104:107], v[140:143], v[204:207], v[104:107]
	v_mfma_f32_16x16x32_bf16 v[100:103], v[132:135], v[212:215], v[100:103]
	v_mfma_f32_16x16x32_bf16 v[96:99], v[140:143], v[212:215], v[96:99]
	s_setprio 0
	s_setprio 1
	v_mfma_f32_16x16x32_bf16 v[92:95], v[144:147], v[160:163], v[92:95]
	v_mfma_f32_16x16x32_bf16 v[88:91], v[152:155], v[160:163], v[88:91]
	v_mfma_f32_16x16x32_bf16 v[84:87], v[144:147], v[168:171], v[84:87]
	v_mfma_f32_16x16x32_bf16 v[80:83], v[152:155], v[168:171], v[80:83]
	v_mfma_f32_16x16x32_bf16 v[76:79], v[144:147], v[200:203], v[76:79]
	v_mfma_f32_16x16x32_bf16 v[72:75], v[152:155], v[200:203], v[72:75]
	v_mfma_f32_16x16x32_bf16 v[68:71], v[144:147], v[208:211], v[68:71]
	v_mfma_f32_16x16x32_bf16 v[64:67], v[152:155], v[208:211], v[64:67]
	v_mfma_f32_16x16x32_bf16 v[92:95], v[148:151], v[164:167], v[92:95]
	v_mfma_f32_16x16x32_bf16 v[88:91], v[156:159], v[164:167], v[88:91]
	v_mfma_f32_16x16x32_bf16 v[84:87], v[148:151], v[172:175], v[84:87]
	v_mfma_f32_16x16x32_bf16 v[80:83], v[156:159], v[172:175], v[80:83]
	v_mfma_f32_16x16x32_bf16 v[76:79], v[148:151], v[204:207], v[76:79]
	v_mfma_f32_16x16x32_bf16 v[72:75], v[156:159], v[204:207], v[72:75]
	v_mfma_f32_16x16x32_bf16 v[68:71], v[148:151], v[212:215], v[68:71]
	v_mfma_f32_16x16x32_bf16 v[64:67], v[156:159], v[212:215], v[64:67]
	s_setprio 0
	s_barrier
; #define PG8_STAGE(bufoff, gbase, voff) do { _Pragma("unroll") for (int _i = 0; _i < 2; ++_i) \
;         __builtin_amdgcn_global_load_lds((const unsigned*)((const char*)(gbase) + (voff)[_i]), (LAS unsigned*)(lds + (bufoff) + ldsw + _i * 8192), 16, 0, 0); } while (0)
; #define PG8_LDA(dst, b, h) do { _Pragma("unroll") for (int m = 0; m < 4; ++m) _Pragma("unroll") for (int k = 0; k < 2; ++k) dst[m][k] = *(const LAS bf16x8*)(lds + PG8_SA(b, h) + aoff + m * 2048 + k * 1024); } while (0)
; #define PG8_WAIT_V(n) asm volatile("s_waitcnt vmcnt(" #n ")" ::: "memory")
; #define PG8_WAIT_L(n) asm volatile("s_waitcnt lgkmcnt(" #n ")" ::: "memory")
; #define PG8_BAR __builtin_amdgcn_s_barrier()
; #define PG8_SCHED __builtin_amdgcn_sched_barrier(0)
; template <class Epi, class Sched, bool F8 = false>
; __device__ __forceinline__ void gemm_phase(LAS unsigned char* lds, const Gemm g, const Sched& S, const Epi& E) {
;     ...
;             PG8_LDA(At, 1, 1); PG8_STAGE(PG8_SB(1, 0), b3, voffB); PG8_STAGE(PG8_SB(1, 1), b3 + hstepB, voffB); PG8_STAGE(PG8_SA(1, 0), a3, voffA);
;             PG8_WAIT_V(8); PG8_WAIT_L(0); PG8_BAR; PG8_MMA(1, 0, At, B0); PG8_MMA(1, 1, At, B1); PG8_BAR; PG8_SCHED;
;         }
;         if (wr == 0) PG8_BAR;
	s_add_i32 s36, s81, s38
	v_lshl_add_u64 v[216:217], v[216:217], 0, s[16:17]
	s_mov_b32 m0, s36
	ds_read_b128 v[160:163], v199 offset:49152
	ds_read_b128 v[164:167], v199 offset:50176
	ds_read_b128 v[168:171], v199 offset:51200
	ds_read_b128 v[172:175], v199 offset:52224
	ds_read_b128 v[200:203], v199 offset:53248
	ds_read_b128 v[204:207], v199 offset:54272
	ds_read_b128 v[208:211], v199 offset:55296
	ds_read_b128 v[212:215], v199 offset:56320
	global_load_lds_dwordx4 v[216:217], off
	s_add_i32 m0, s36, 0x2000
	s_add_u32 s34, s34, 0x80080
	v_lshl_add_u64 v[216:217], v[218:219], 0, s[16:17]
	s_addc_u32 s35, s35, 0
	s_add_i32 s36, s82, s38
	global_load_lds_dwordx4 v[216:217], off
	s_mov_b32 m0, s36
	s_nop 0
	global_load_lds_dwordx4 v180, s[34:35]
	s_add_i32 m0, s36, 0x2000
	s_nop 0
	global_load_lds_dwordx4 v176, s[34:35]
	v_lshl_add_u64 v[216:217], v[220:221], 0, s[16:17]
	s_mov_b32 m0, s45
	s_nop 0
	global_load_lds_dwordx4 v[216:217], off
	v_lshl_add_u64 v[216:217], v[222:223], 0, s[16:17]
	s_mov_b32 m0, s47
	s_nop 0
	global_load_lds_dwordx4 v[216:217], off
	s_waitcnt vmcnt(8)
	s_waitcnt lgkmcnt(0)
	s_barrier
	s_setprio 1
	s_waitcnt lgkmcnt(0)
	v_mfma_f32_16x16x32_bf16 v[60:63], v[128:131], v[160:163], v[60:63]
	v_mfma_f32_16x16x32_bf16 v[56:59], v[136:139], v[160:163], v[56:59]
	v_mfma_f32_16x16x32_bf16 v[52:55], v[128:131], v[168:171], v[52:55]
	v_mfma_f32_16x16x32_bf16 v[48:51], v[136:139], v[168:171], v[48:51]
	v_mfma_f32_16x16x32_bf16 v[44:47], v[128:131], v[200:203], v[44:47]
	v_mfma_f32_16x16x32_bf16 v[40:43], v[136:139], v[200:203], v[40:43]
	v_mfma_f32_16x16x32_bf16 v[36:39], v[128:131], v[208:211], v[36:39]
	v_mfma_f32_16x16x32_bf16 v[32:35], v[136:139], v[208:211], v[32:35]
	v_mfma_f32_16x16x32_bf16 v[60:63], v[132:135], v[164:167], v[60:63]
	v_mfma_f32_16x16x32_bf16 v[56:59], v[140:143], v[164:167], v[56:59]
	v_mfma_f32_16x16x32_bf16 v[52:55], v[132:135], v[172:175], v[52:55]
	v_mfma_f32_16x16x32_bf16 v[48:51], v[140:143], v[172:175], v[48:51]
	v_mfma_f32_16x16x32_bf16 v[44:47], v[132:135], v[204:207], v[44:47]
	v_mfma_f32_16x16x32_bf16 v[40:43], v[140:143], v[204:207], v[40:43]
	v_mfma_f32_16x16x32_bf16 v[36:39], v[132:135], v[212:215], v[36:39]
	v_mfma_f32_16x16x32_bf16 v[32:35], v[140:143], v[212:215], v[32:35]
	s_setprio 0
	s_setprio 1
	v_mfma_f32_16x16x32_bf16 v[28:31], v[144:147], v[160:163], v[28:31]
	v_mfma_f32_16x16x32_bf16 v[24:27], v[152:155], v[160:163], v[24:27]
	v_mfma_f32_16x16x32_bf16 v[20:23], v[144:147], v[168:171], v[20:23]
	v_mfma_f32_16x16x32_bf16 v[16:19], v[152:155], v[168:171], v[16:19]
	v_mfma_f32_16x16x32_bf16 v[12:15], v[144:147], v[200:203], v[12:15]
	v_mfma_f32_16x16x32_bf16 v[8:11], v[152:155], v[200:203], v[8:11]
	v_mfma_f32_16x16x32_bf16 v[4:7], v[144:147], v[208:211], v[4:7]
	v_mfma_f32_16x16x32_bf16 v[0:3], v[152:155], v[208:211], v[0:3]
	v_mfma_f32_16x16x32_bf16 v[28:31], v[148:151], v[164:167], v[28:31]
	v_mfma_f32_16x16x32_bf16 v[24:27], v[156:159], v[164:167], v[24:27]
	v_mfma_f32_16x16x32_bf16 v[20:23], v[148:151], v[172:175], v[20:23]
	v_mfma_f32_16x16x32_bf16 v[16:19], v[156:159], v[172:175], v[16:19]
	v_mfma_f32_16x16x32_bf16 v[12:15], v[148:151], v[204:207], v[12:15]
	v_mfma_f32_16x16x32_bf16 v[8:11], v[156:159], v[204:207], v[8:11]
	v_mfma_f32_16x16x32_bf16 v[4:7], v[148:151], v[212:215], v[4:7]
	v_mfma_f32_16x16x32_bf16 v[0:3], v[156:159], v[212:215], v[0:3]
	s_setprio 0
	s_barrier
	s_add_u32 s30, s30, 0x100
	s_addc_u32 s31, s31, 0
	s_add_u32 s78, s78, 0x100
	s_addc_u32 s79, s79, 0
	s_cmp_ge_i32 s80, s9
	s_mov_b32 s34, s80
	s_cbranch_scc0 .LBB0_753
	s_and_b64 vcc, exec, s[18:19]
	s_cbranch_vccz .LBB0_756
	s_barrier

; #define PG8_STAGE(bufoff, gbase, voff) do { _Pragma("unroll") for (int _i = 0; _i < 2; ++_i) \
;         __builtin_amdgcn_global_load_lds((const unsigned*)((const char*)(gbase) + (voff)[_i]), (LAS unsigned*)(lds + (bufoff) + ldsw + _i * 8192), 16, 0, 0); } while (0)
; #define PG8_LDA(dst, b, h) do { _Pragma("unroll") for (int m = 0; m < 4; ++m) _Pragma("unroll") for (int k = 0; k < 2; ++k) dst[m][k] = *(const LAS bf16x8*)(lds + PG8_SA(b, h) + aoff + m * 2048 + k * 1024); } while (0)
; #define PG8_LDB(dst, b, h) do { _Pragma("unroll") for (int n = 0; n < 2; ++n) _Pragma("unroll") for (int k = 0; k < 2; ++k) dst[n][k] = *(const LAS bf16x8*)(lds + PG8_SB(b, h) + boff + n * 2048 + k * 1024); } while (0)
; #define PG8_WAIT_V(n) asm volatile("s_waitcnt vmcnt(" #n ")" ::: "memory")
; #define PG8_WAIT_L(n) asm volatile("s_waitcnt lgkmcnt(" #n ")" ::: "memory")
; #define PG8_BAR __builtin_amdgcn_s_barrier()
; #define PG8_SCHED __builtin_amdgcn_sched_barrier(0)
; template <class Epi, class Sched, bool F8 = false>
; __device__ __forceinline__ void gemm_phase(LAS unsigned char* lds, const Gemm g, const Sched& S, const Epi& E) {
;     ...
;         for (int t = 0; t < nt; t += 2) {
;             const bool last = (t == nt - 2);
;             const char* a1 = cA + (size_t)(t + 1) * kstep;
;             const char* a2 = last ? nA : cA + (size_t)(t + 2) * kstep; const char* b2 = last ? nB : cB + (size_t)(t + 2) * kstep;
;             const char* a3 = a2 + kstep; const char* b3 = b2 + kstep;
;             PG8_LDB(B0, 0, 0); PG8_LDB(B1, 0, 1); PG8_SCHED; PG8_LDA(At, 0, 0); PG8_STAGE(PG8_SA(1, 1), a1 + hstepA, voffA);
;             PG8_WAIT_V(8); PG8_WAIT_L(0); PG8_BAR; PG8_MMA(0, 0, At, B0); PG8_MMA(0, 1, At, B1); PG8_BAR; PG8_SCHED;
;             PG8_LDA(At, 0, 1); PG8_STAGE(PG8_SB(0, 0), b2, voffB); PG8_STAGE(PG8_SB(0, 1), b2 + hstepB, voffB); PG8_STAGE(PG8_SA(0, 0), a2, voffA);
;             PG8_WAIT_V(8); PG8_WAIT_L(0); PG8_BAR; PG8_MMA(1, 0, At, B0); PG8_MMA(1, 1, At, B1); PG8_BAR; PG8_SCHED;
.LBB0_825:
	ds_read_b128 v[168:171], v164
	ds_read_b128 v[172:175], v164 offset:1024
	ds_read_b128 v[176:179], v164 offset:2048
	ds_read_b128 v[180:183], v164 offset:3072
	ds_read_b128 v[184:187], v165
	ds_read_b128 v[192:195], v165 offset:1024
	ds_read_b128 v[196:199], v165 offset:2048
	ds_read_b128 v[200:203], v165 offset:3072
	s_add_u32 s38, s36, 0xfff80080
	s_addc_u32 s39, s37, -1
	s_cmp_eq_u32 s58, 28
	s_cselect_b32 s41, s10, s39
	s_cselect_b32 s40, s27, s38
	s_cselect_b32 s39, s25, s57
	s_cselect_b32 s38, s35, s56
	s_add_i32 m0, s43, 0xc000
	ds_read_b128 v[204:207], v166
	ds_read_b128 v[208:211], v166 offset:1024
	ds_read_b128 v[212:215], v166 offset:2048
	ds_read_b128 v[216:219], v166 offset:3072
	ds_read_b128 v[220:223], v166 offset:4096
	ds_read_b128 v[224:227], v166 offset:5120
	ds_read_b128 v[228:231], v166 offset:6144
	ds_read_b128 v[232:235], v166 offset:7168
	global_load_lds_dwordx4 v152, s[36:37]
	s_add_i32 m0, s43, 0xe000
	s_nop 0
	global_load_lds_dwordx4 v154, s[36:37]
	s_waitcnt vmcnt(8)
	s_waitcnt lgkmcnt(0)
	s_barrier
	s_setprio 1
	s_waitcnt lgkmcnt(0)
	v_mfma_f32_16x16x32_bf16 v[124:127], v[168:171], v[204:207], v[124:127]
	v_mfma_f32_16x16x32_bf16 v[120:123], v[176:179], v[204:207], v[120:123]
	v_mfma_f32_16x16x32_bf16 v[116:119], v[168:171], v[212:215], v[116:119]
	v_mfma_f32_16x16x32_bf16 v[108:111], v[176:179], v[212:215], v[108:111]
	v_mfma_f32_16x16x32_bf16 v[100:103], v[168:171], v[220:223], v[100:103]
	v_mfma_f32_16x16x32_bf16 v[92:95], v[176:179], v[220:223], v[92:95]
	v_mfma_f32_16x16x32_bf16 v[84:87], v[168:171], v[228:231], v[84:87]
	v_mfma_f32_16x16x32_bf16 v[76:79], v[176:179], v[228:231], v[76:79]
	v_mfma_f32_16x16x32_bf16 v[124:127], v[172:175], v[208:211], v[124:127]
	v_mfma_f32_16x16x32_bf16 v[120:123], v[180:183], v[208:211], v[120:123]
	v_mfma_f32_16x16x32_bf16 v[116:119], v[172:175], v[216:219], v[116:119]
	v_mfma_f32_16x16x32_bf16 v[108:111], v[180:183], v[216:219], v[108:111]
	v_mfma_f32_16x16x32_bf16 v[100:103], v[172:175], v[224:227], v[100:103]
	v_mfma_f32_16x16x32_bf16 v[92:95], v[180:183], v[224:227], v[92:95]
	v_mfma_f32_16x16x32_bf16 v[84:87], v[172:175], v[232:235], v[84:87]
	v_mfma_f32_16x16x32_bf16 v[76:79], v[180:183], v[232:235], v[76:79]
	s_setprio 0
	s_setprio 1
	v_mfma_f32_16x16x32_bf16 v[112:115], v[184:187], v[204:207], v[112:115]
	v_mfma_f32_16x16x32_bf16 v[104:107], v[196:199], v[204:207], v[104:107]
	v_mfma_f32_16x16x32_bf16 v[96:99], v[184:187], v[212:215], v[96:99]
	v_mfma_f32_16x16x32_bf16 v[88:91], v[196:199], v[212:215], v[88:91]
	v_mfma_f32_16x16x32_bf16 v[80:83], v[184:187], v[220:223], v[80:83]
	v_mfma_f32_16x16x32_bf16 v[72:75], v[196:199], v[220:223], v[72:75]
	v_mfma_f32_16x16x32_bf16 v[68:71], v[184:187], v[228:231], v[68:71]
	v_mfma_f32_16x16x32_bf16 v[64:67], v[196:199], v[228:231], v[64:67]
	v_mfma_f32_16x16x32_bf16 v[112:115], v[192:195], v[208:211], v[112:115]
	v_mfma_f32_16x16x32_bf16 v[104:107], v[200:203], v[208:211], v[104:107]
	v_mfma_f32_16x16x32_bf16 v[96:99], v[192:195], v[216:219], v[96:99]
	v_mfma_f32_16x16x32_bf16 v[88:91], v[200:203], v[216:219], v[88:91]
	v_mfma_f32_16x16x32_bf16 v[80:83], v[192:195], v[224:227], v[80:83]
	v_mfma_f32_16x16x32_bf16 v[72:75], v[200:203], v[224:227], v[72:75]
	v_mfma_f32_16x16x32_bf16 v[68:71], v[192:195], v[232:235], v[68:71]
	v_mfma_f32_16x16x32_bf16 v[64:67], v[200:203], v[232:235], v[64:67]
	s_setprio 0
	s_barrier
	s_add_i32 s59, s50, s23
	v_lshl_add_u64 v[160:161], s[38:39], 0, v[132:133]
	s_mov_b32 m0, s59
	ds_read_b128 v[204:207], v166 offset:16384
	ds_read_b128 v[208:211], v166 offset:17408
	ds_read_b128 v[212:215], v166 offset:18432
	ds_read_b128 v[216:219], v166 offset:19456
	ds_read_b128 v[220:223], v166 offset:20480
	ds_read_b128 v[224:227], v166 offset:21504
	ds_read_b128 v[228:231], v166 offset:22528
	ds_read_b128 v[232:235], v166 offset:23552
	global_load_lds_dwordx4 v[160:161], off
	s_add_i32 m0, s59, 0x2000
	s_add_u32 s72, s38, 0x80000
	v_lshl_add_u64 v[188:189], s[38:39], 0, v[128:129]
	s_addc_u32 s73, s39, 0
	s_add_i32 s59, s91, s23
	global_load_lds_dwordx4 v[188:189], off
	s_mov_b32 m0, s59
	v_lshl_add_u64 v[238:239], s[40:41], 0, v[130:131]
	global_load_lds_dwordx4 v132, s[72:73]
	s_add_i32 m0, s59, 0x2000
	s_nop 0
	global_load_lds_dwordx4 v128, s[72:73]
	v_lshl_add_u64 v[236:237], s[40:41], 0, v[134:135]
	s_mov_b32 m0, s43
	s_nop 0
	global_load_lds_dwordx4 v[236:237], off
	s_mov_b32 m0, s44
	s_nop 0
	global_load_lds_dwordx4 v[238:239], off
	s_waitcnt vmcnt(8)
	s_waitcnt lgkmcnt(0)
	s_barrier
; #define PG8_STAGE(bufoff, gbase, voff) do { _Pragma("unroll") for (int _i = 0; _i < 2; ++_i) \
;         __builtin_amdgcn_global_load_lds((const unsigned*)((const char*)(gbase) + (voff)[_i]), (LAS unsigned*)(lds + (bufoff) + ldsw + _i * 8192), 16, 0, 0); } while (0)
; #define PG8_LDA(dst, b, h) do { _Pragma("unroll") for (int m = 0; m < 4; ++m) _Pragma("unroll") for (int k = 0; k < 2; ++k) dst[m][k] = *(const LAS bf16x8*)(lds + PG8_SA(b, h) + aoff + m * 2048 + k * 1024); } while (0)
; #define PG8_LDB(dst, b, h) do { _Pragma("unroll") for (int n = 0; n < 2; ++n) _Pragma("unroll") for (int k = 0; k < 2; ++k) dst[n][k] = *(const LAS bf16x8*)(lds + PG8_SB(b, h) + boff + n * 2048 + k * 1024); } while (0)
; #define PG8_WAIT_V(n) asm volatile("s_waitcnt vmcnt(" #n ")" ::: "memory")
; #define PG8_WAIT_L(n) asm volatile("s_waitcnt lgkmcnt(" #n ")" ::: "memory")
; #define PG8_BAR __builtin_amdgcn_s_barrier()
; #define PG8_SCHED __builtin_amdgcn_sched_barrier(0)
; template <class Epi, class Sched, bool F8 = false>
; __device__ __forceinline__ void gemm_phase(LAS unsigned char* lds, const Gemm g, const Sched& S, const Epi& E) {
;     ...
;             PG8_WAIT_V(8); PG8_WAIT_L(0); PG8_BAR; PG8_MMA(1, 0, At, B0); PG8_MMA(1, 1, At, B1); PG8_BAR; PG8_SCHED;
;             PG8_LDB(B0, 1, 0); PG8_LDB(B1, 1, 1); PG8_SCHED; PG8_LDA(At, 1, 0); PG8_STAGE(PG8_SA(0, 1), a2 + hstepA, voffA);
;             PG8_WAIT_V(8); PG8_WAIT_L(0); PG8_BAR; PG8_MMA(0, 0, At, B0); PG8_MMA(0, 1, At, B1); PG8_BAR; PG8_SCHED;
	s_setprio 1
	s_waitcnt lgkmcnt(0)
	v_mfma_f32_16x16x32_bf16 v[60:63], v[168:171], v[204:207], v[60:63]
	v_mfma_f32_16x16x32_bf16 v[56:59], v[176:179], v[204:207], v[56:59]
	v_mfma_f32_16x16x32_bf16 v[52:55], v[168:171], v[212:215], v[52:55]
	v_mfma_f32_16x16x32_bf16 v[44:47], v[176:179], v[212:215], v[44:47]
	v_mfma_f32_16x16x32_bf16 v[36:39], v[168:171], v[220:223], v[36:39]
	v_mfma_f32_16x16x32_bf16 v[28:31], v[176:179], v[220:223], v[28:31]
	v_mfma_f32_16x16x32_bf16 v[20:23], v[168:171], v[228:231], v[20:23]
	v_mfma_f32_16x16x32_bf16 v[12:15], v[176:179], v[228:231], v[12:15]
	v_mfma_f32_16x16x32_bf16 v[60:63], v[172:175], v[208:211], v[60:63]
	v_mfma_f32_16x16x32_bf16 v[56:59], v[180:183], v[208:211], v[56:59]
	v_mfma_f32_16x16x32_bf16 v[52:55], v[172:175], v[216:219], v[52:55]
	v_mfma_f32_16x16x32_bf16 v[44:47], v[180:183], v[216:219], v[44:47]
	v_mfma_f32_16x16x32_bf16 v[36:39], v[172:175], v[224:227], v[36:39]
	v_mfma_f32_16x16x32_bf16 v[28:31], v[180:183], v[224:227], v[28:31]
	v_mfma_f32_16x16x32_bf16 v[20:23], v[172:175], v[232:235], v[20:23]
	v_mfma_f32_16x16x32_bf16 v[12:15], v[180:183], v[232:235], v[12:15]
	s_setprio 0
	s_setprio 1
	v_mfma_f32_16x16x32_bf16 v[48:51], v[184:187], v[204:207], v[48:51]
	v_mfma_f32_16x16x32_bf16 v[40:43], v[196:199], v[204:207], v[40:43]
	v_mfma_f32_16x16x32_bf16 v[32:35], v[184:187], v[212:215], v[32:35]
	v_mfma_f32_16x16x32_bf16 v[24:27], v[196:199], v[212:215], v[24:27]
	v_mfma_f32_16x16x32_bf16 v[16:19], v[184:187], v[220:223], v[16:19]
	v_mfma_f32_16x16x32_bf16 v[8:11], v[196:199], v[220:223], v[8:11]
	v_mfma_f32_16x16x32_bf16 v[4:7], v[184:187], v[228:231], v[4:7]
	v_mfma_f32_16x16x32_bf16 v[0:3], v[196:199], v[228:231], v[0:3]
	v_mfma_f32_16x16x32_bf16 v[48:51], v[192:195], v[208:211], v[48:51]
	v_mfma_f32_16x16x32_bf16 v[40:43], v[200:203], v[208:211], v[40:43]
	v_mfma_f32_16x16x32_bf16 v[32:35], v[192:195], v[216:219], v[32:35]
	v_mfma_f32_16x16x32_bf16 v[24:27], v[200:203], v[216:219], v[24:27]
	v_mfma_f32_16x16x32_bf16 v[16:19], v[192:195], v[224:227], v[16:19]
	v_mfma_f32_16x16x32_bf16 v[8:11], v[200:203], v[224:227], v[8:11]
	v_mfma_f32_16x16x32_bf16 v[4:7], v[192:195], v[232:235], v[4:7]
	v_mfma_f32_16x16x32_bf16 v[0:3], v[200:203], v[232:235], v[0:3]
	s_setprio 0
	s_barrier
	s_add_i32 s59, 0, 0x18000
	v_add_u32_e32 v167, s59, v162
	s_add_i32 s72, 0, 0x1c000
	ds_read_b128 v[168:171], v167
	ds_read_b128 v[172:175], v167 offset:1024
	ds_read_b128 v[176:179], v167 offset:2048
	ds_read_b128 v[180:183], v167 offset:3072
	v_add_u32_e32 v167, s72, v162
	ds_read_b128 v[184:187], v167
	ds_read_b128 v[192:195], v167 offset:1024
	ds_read_b128 v[196:199], v167 offset:2048
	ds_read_b128 v[200:203], v167 offset:3072
	s_add_u32 s40, s40, 0x80000
	s_addc_u32 s41, s41, 0
	s_mov_b32 m0, s45
	ds_read_b128 v[204:207], v166 offset:32768
	ds_read_b128 v[208:211], v166 offset:33792
	ds_read_b128 v[212:215], v166 offset:34816
	ds_read_b128 v[216:219], v166 offset:35840
	ds_read_b128 v[220:223], v166 offset:36864
	ds_read_b128 v[224:227], v166 offset:37888
	ds_read_b128 v[228:231], v166 offset:38912
	ds_read_b128 v[232:235], v166 offset:39936
	global_load_lds_dwordx4 v134, s[40:41]
	s_mov_b32 m0, s47
	s_nop 0
	global_load_lds_dwordx4 v130, s[40:41]
	s_waitcnt vmcnt(8)
	s_waitcnt lgkmcnt(0)
	s_barrier
	s_setprio 1
	s_waitcnt lgkmcnt(0)
	v_mfma_f32_16x16x32_bf16 v[124:127], v[168:171], v[204:207], v[124:127]
	v_mfma_f32_16x16x32_bf16 v[120:123], v[176:179], v[204:207], v[120:123]
	v_mfma_f32_16x16x32_bf16 v[116:119], v[168:171], v[212:215], v[116:119]
	v_mfma_f32_16x16x32_bf16 v[108:111], v[176:179], v[212:215], v[108:111]
	v_mfma_f32_16x16x32_bf16 v[100:103], v[168:171], v[220:223], v[100:103]
	v_mfma_f32_16x16x32_bf16 v[92:95], v[176:179], v[220:223], v[92:95]
	v_mfma_f32_16x16x32_bf16 v[84:87], v[168:171], v[228:231], v[84:87]
	v_mfma_f32_16x16x32_bf16 v[76:79], v[176:179], v[228:231], v[76:79]
	v_mfma_f32_16x16x32_bf16 v[124:127], v[172:175], v[208:211], v[124:127]
	v_mfma_f32_16x16x32_bf16 v[120:123], v[180:183], v[208:211], v[120:123]
	v_mfma_f32_16x16x32_bf16 v[116:119], v[172:175], v[216:219], v[116:119]
	v_mfma_f32_16x16x32_bf16 v[108:111], v[180:183], v[216:219], v[108:111]
	v_mfma_f32_16x16x32_bf16 v[100:103], v[172:175], v[224:227], v[100:103]
	v_mfma_f32_16x16x32_bf16 v[92:95], v[180:183], v[224:227], v[92:95]
	v_mfma_f32_16x16x32_bf16 v[84:87], v[172:175], v[232:235], v[84:87]
	v_mfma_f32_16x16x32_bf16 v[76:79], v[180:183], v[232:235], v[76:79]
	s_setprio 0
	s_setprio 1
	v_mfma_f32_16x16x32_bf16 v[112:115], v[184:187], v[204:207], v[112:115]
	v_mfma_f32_16x16x32_bf16 v[104:107], v[196:199], v[204:207], v[104:107]
	v_mfma_f32_16x16x32_bf16 v[96:99], v[184:187], v[212:215], v[96:99]
	v_mfma_f32_16x16x32_bf16 v[88:91], v[196:199], v[212:215], v[88:91]
	v_mfma_f32_16x16x32_bf16 v[80:83], v[184:187], v[220:223], v[80:83]
	v_mfma_f32_16x16x32_bf16 v[72:75], v[196:199], v[220:223], v[72:75]
	v_mfma_f32_16x16x32_bf16 v[68:71], v[184:187], v[228:231], v[68:71]
	v_mfma_f32_16x16x32_bf16 v[64:67], v[196:199], v[228:231], v[64:67]
	v_mfma_f32_16x16x32_bf16 v[112:115], v[192:195], v[208:211], v[112:115]
	v_mfma_f32_16x16x32_bf16 v[104:107], v[200:203], v[208:211], v[104:107]
	v_mfma_f32_16x16x32_bf16 v[96:99], v[192:195], v[216:219], v[96:99]
	v_mfma_f32_16x16x32_bf16 v[88:91], v[200:203], v[216:219], v[88:91]
	v_mfma_f32_16x16x32_bf16 v[80:83], v[192:195], v[224:227], v[80:83]
	v_mfma_f32_16x16x32_bf16 v[72:75], v[200:203], v[224:227], v[72:75]
	v_mfma_f32_16x16x32_bf16 v[68:71], v[192:195], v[232:235], v[68:71]
	v_mfma_f32_16x16x32_bf16 v[64:67], v[200:203], v[232:235], v[64:67]
	s_setprio 0
	s_barrier
; #define PG8_STAGE(bufoff, gbase, voff) do { _Pragma("unroll") for (int _i = 0; _i < 2; ++_i) \
;         __builtin_amdgcn_global_load_lds((const unsigned*)((const char*)(gbase) + (voff)[_i]), (LAS unsigned*)(lds + (bufoff) + ldsw + _i * 8192), 16, 0, 0); } while (0)
; #define PG8_LDA(dst, b, h) do { _Pragma("unroll") for (int m = 0; m < 4; ++m) _Pragma("unroll") for (int k = 0; k < 2; ++k) dst[m][k] = *(const LAS bf16x8*)(lds + PG8_SA(b, h) + aoff + m * 2048 + k * 1024); } while (0)
; #define PG8_WAIT_V(n) asm volatile("s_waitcnt vmcnt(" #n ")" ::: "memory")
; #define PG8_WAIT_L(n) asm volatile("s_waitcnt lgkmcnt(" #n ")" ::: "memory")
; #define PG8_BAR __builtin_amdgcn_s_barrier()
; #define PG8_SCHED __builtin_amdgcn_sched_barrier(0)
; template <class Epi, class Sched, bool F8 = false>
; __device__ __forceinline__ void gemm_phase(LAS unsigned char* lds, const Gemm g, const Sched& S, const Epi& E) {
;     ...
;             PG8_LDA(At, 1, 1); PG8_STAGE(PG8_SB(1, 0), b3, voffB); PG8_STAGE(PG8_SB(1, 1), b3 + hstepB, voffB); PG8_STAGE(PG8_SA(1, 0), a3, voffA);
;             PG8_WAIT_V(8); PG8_WAIT_L(0); PG8_BAR; PG8_MMA(1, 0, At, B0); PG8_MMA(1, 1, At, B1); PG8_BAR; PG8_SCHED;
;         }
;         if (wr == 0) PG8_BAR;
	s_add_i32 s40, s59, s23
	v_lshl_add_u64 v[160:161], v[160:161], 0, s[18:19]
	s_mov_b32 m0, s40
	ds_read_b128 v[204:207], v166 offset:49152
	ds_read_b128 v[208:211], v166 offset:50176
	ds_read_b128 v[212:215], v166 offset:51200
	ds_read_b128 v[216:219], v166 offset:52224
	ds_read_b128 v[220:223], v166 offset:53248
	ds_read_b128 v[224:227], v166 offset:54272
	ds_read_b128 v[228:231], v166 offset:55296
	ds_read_b128 v[232:235], v166 offset:56320
	global_load_lds_dwordx4 v[160:161], off
	s_add_i32 m0, s40, 0x2000
	s_add_u32 s38, s38, 0x80080
	v_lshl_add_u64 v[160:161], v[188:189], 0, s[18:19]
	s_addc_u32 s39, s39, 0
	s_add_i32 s40, s72, s23
	global_load_lds_dwordx4 v[160:161], off
	s_mov_b32 m0, s40
	s_nop 0
	global_load_lds_dwordx4 v132, s[38:39]
	s_add_i32 m0, s40, 0x2000
	s_nop 0
	global_load_lds_dwordx4 v128, s[38:39]
	v_lshl_add_u64 v[160:161], v[236:237], 0, s[18:19]
	s_mov_b32 m0, s48
	s_nop 0
	global_load_lds_dwordx4 v[160:161], off
	v_lshl_add_u64 v[160:161], v[238:239], 0, s[18:19]
	s_mov_b32 m0, s49
	s_nop 0
	global_load_lds_dwordx4 v[160:161], off
	s_waitcnt vmcnt(8)
	s_waitcnt lgkmcnt(0)
	s_barrier
	s_setprio 1
	s_waitcnt lgkmcnt(0)
	v_mfma_f32_16x16x32_bf16 v[60:63], v[168:171], v[204:207], v[60:63]
	v_mfma_f32_16x16x32_bf16 v[56:59], v[176:179], v[204:207], v[56:59]
	v_mfma_f32_16x16x32_bf16 v[52:55], v[168:171], v[212:215], v[52:55]
	v_mfma_f32_16x16x32_bf16 v[44:47], v[176:179], v[212:215], v[44:47]
	v_mfma_f32_16x16x32_bf16 v[36:39], v[168:171], v[220:223], v[36:39]
	v_mfma_f32_16x16x32_bf16 v[28:31], v[176:179], v[220:223], v[28:31]
	v_mfma_f32_16x16x32_bf16 v[20:23], v[168:171], v[228:231], v[20:23]
	v_mfma_f32_16x16x32_bf16 v[12:15], v[176:179], v[228:231], v[12:15]
	v_mfma_f32_16x16x32_bf16 v[60:63], v[172:175], v[208:211], v[60:63]
	v_mfma_f32_16x16x32_bf16 v[56:59], v[180:183], v[208:211], v[56:59]
	v_mfma_f32_16x16x32_bf16 v[52:55], v[172:175], v[216:219], v[52:55]
	v_mfma_f32_16x16x32_bf16 v[44:47], v[180:183], v[216:219], v[44:47]
	v_mfma_f32_16x16x32_bf16 v[36:39], v[172:175], v[224:227], v[36:39]
	v_mfma_f32_16x16x32_bf16 v[28:31], v[180:183], v[224:227], v[28:31]
	v_mfma_f32_16x16x32_bf16 v[20:23], v[172:175], v[232:235], v[20:23]
	v_mfma_f32_16x16x32_bf16 v[12:15], v[180:183], v[232:235], v[12:15]
	s_setprio 0
	s_setprio 1
	v_mfma_f32_16x16x32_bf16 v[48:51], v[184:187], v[204:207], v[48:51]
	v_mfma_f32_16x16x32_bf16 v[40:43], v[196:199], v[204:207], v[40:43]
	v_mfma_f32_16x16x32_bf16 v[32:35], v[184:187], v[212:215], v[32:35]
	v_mfma_f32_16x16x32_bf16 v[24:27], v[196:199], v[212:215], v[24:27]
	v_mfma_f32_16x16x32_bf16 v[16:19], v[184:187], v[220:223], v[16:19]
	v_mfma_f32_16x16x32_bf16 v[8:11], v[196:199], v[220:223], v[8:11]
	v_mfma_f32_16x16x32_bf16 v[4:7], v[184:187], v[228:231], v[4:7]
	v_mfma_f32_16x16x32_bf16 v[0:3], v[196:199], v[228:231], v[0:3]
	v_mfma_f32_16x16x32_bf16 v[48:51], v[192:195], v[208:211], v[48:51]
	v_mfma_f32_16x16x32_bf16 v[40:43], v[200:203], v[208:211], v[40:43]
	v_mfma_f32_16x16x32_bf16 v[32:35], v[192:195], v[216:219], v[32:35]
	v_mfma_f32_16x16x32_bf16 v[24:27], v[200:203], v[216:219], v[24:27]
	v_mfma_f32_16x16x32_bf16 v[16:19], v[192:195], v[224:227], v[16:19]
	v_mfma_f32_16x16x32_bf16 v[8:11], v[200:203], v[224:227], v[8:11]
	v_mfma_f32_16x16x32_bf16 v[4:7], v[192:195], v[232:235], v[4:7]
	v_mfma_f32_16x16x32_bf16 v[0:3], v[200:203], v[232:235], v[0:3]
	s_setprio 0
	s_barrier
	s_add_i32 s58, s58, 2
	s_add_u32 s36, s36, 0x100
	s_addc_u32 s37, s37, 0
	s_add_u32 s56, s56, 0x100
	s_addc_u32 s57, s57, 0
	s_cmp_gt_u32 s58, 29
	s_cbranch_scc0 .LBB0_825
	s_and_b64 vcc, exec, s[20:21]
	s_cbranch_vccz .LBB0_828
	s_barrier

; #define PG8_STAGE(bufoff, gbase, voff) do { _Pragma("unroll") for (int _i = 0; _i < 2; ++_i) \
;         __builtin_amdgcn_global_load_lds((const unsigned*)((const char*)(gbase) + (voff)[_i]), (LAS unsigned*)(lds + (bufoff) + ldsw + _i * 8192), 16, 0, 0); } while (0)
; #define PG8_LDA(dst, b, h) do { _Pragma("unroll") for (int m = 0; m < 4; ++m) _Pragma("unroll") for (int k = 0; k < 2; ++k) dst[m][k] = *(const LAS bf16x8*)(lds + PG8_SA(b, h) + aoff + m * 2048 + k * 1024); } while (0)
; #define PG8_LDB(dst, b, h) do { _Pragma("unroll") for (int n = 0; n < 2; ++n) _Pragma("unroll") for (int k = 0; k < 2; ++k) dst[n][k] = *(const LAS bf16x8*)(lds + PG8_SB(b, h) + boff + n * 2048 + k * 1024); } while (0)
; #define PG8_WAIT_V(n) asm volatile("s_waitcnt vmcnt(" #n ")" ::: "memory")
; #define PG8_WAIT_L(n) asm volatile("s_waitcnt lgkmcnt(" #n ")" ::: "memory")
; #define PG8_BAR __builtin_amdgcn_s_barrier()
; #define PG8_SCHED __builtin_amdgcn_sched_barrier(0)
; template <class Epi, class Sched, bool F8 = false>
; __device__ __forceinline__ void gemm_phase(LAS unsigned char* lds, const Gemm g, const Sched& S, const Epi& E) {
;     ...
;         for (int t = 0; t < nt; t += 2) {
;             const bool last = (t == nt - 2);
;             const char* a1 = cA + (size_t)(t + 1) * kstep;
;             const char* a2 = last ? nA : cA + (size_t)(t + 2) * kstep; const char* b2 = last ? nB : cB + (size_t)(t + 2) * kstep;
;             const char* a3 = a2 + kstep; const char* b3 = b2 + kstep;
;             PG8_LDB(B0, 0, 0); PG8_LDB(B1, 0, 1); PG8_SCHED; PG8_LDA(At, 0, 0); PG8_STAGE(PG8_SA(1, 1), a1 + hstepA, voffA);
;             PG8_WAIT_V(8); PG8_WAIT_L(0); PG8_BAR; PG8_MMA(0, 0, At, B0); PG8_MMA(0, 1, At, B1); PG8_BAR; PG8_SCHED;
;             PG8_LDA(At, 0, 1); PG8_STAGE(PG8_SB(0, 0), b2, voffB); PG8_STAGE(PG8_SB(0, 1), b2 + hstepB, voffB); PG8_STAGE(PG8_SA(0, 0), a2, voffA);
;             PG8_WAIT_V(8); PG8_WAIT_L(0); PG8_BAR; PG8_MMA(1, 0, At, B0); PG8_MMA(1, 1, At, B1); PG8_BAR; PG8_SCHED;
.LBB0_954:
	ds_read_b128 v[150:153], v147
	ds_read_b128 v[154:157], v147 offset:1024
	ds_read_b128 v[158:161], v147 offset:2048
	ds_read_b128 v[162:165], v147 offset:3072
	ds_read_b128 v[166:169], v148
	ds_read_b128 v[170:173], v148 offset:1024
	ds_read_b128 v[174:177], v148 offset:2048
	ds_read_b128 v[178:181], v148 offset:3072
	s_add_u32 s30, s28, 0xfff80080
	s_addc_u32 s31, s29, -1
	s_cmp_eq_u32 s53, 28
	s_cselect_b32 s35, s21, s31
	s_cselect_b32 s34, s48, s30
	s_cselect_b32 s31, s19, s51
	s_cselect_b32 s30, s49, s50
	s_add_i32 m0, s27, 0xc000
	ds_read_b128 v[182:185], v149
	ds_read_b128 v[186:189], v149 offset:1024
	ds_read_b128 v[192:195], v149 offset:2048
	ds_read_b128 v[196:199], v149 offset:3072
	ds_read_b128 v[200:203], v149 offset:4096
	ds_read_b128 v[204:207], v149 offset:5120
	ds_read_b128 v[208:211], v149 offset:6144
	ds_read_b128 v[212:215], v149 offset:7168
	global_load_lds_dwordx4 v136, s[28:29]
	s_add_i32 m0, s27, 0xe000
	s_nop 0
	global_load_lds_dwordx4 v138, s[28:29]
	s_waitcnt vmcnt(8)
	s_waitcnt lgkmcnt(0)
	s_barrier
	s_setprio 1
	s_waitcnt lgkmcnt(0)
	v_mfma_f32_16x16x32_bf16 v[124:127], v[150:153], v[182:185], v[124:127]
	v_mfma_f32_16x16x32_bf16 v[120:123], v[158:161], v[182:185], v[120:123]
	v_mfma_f32_16x16x32_bf16 v[108:111], v[150:153], v[192:195], v[108:111]
	v_mfma_f32_16x16x32_bf16 v[104:107], v[158:161], v[192:195], v[104:107]
	v_mfma_f32_16x16x32_bf16 v[92:95], v[150:153], v[200:203], v[92:95]
	v_mfma_f32_16x16x32_bf16 v[88:91], v[158:161], v[200:203], v[88:91]
	v_mfma_f32_16x16x32_bf16 v[76:79], v[150:153], v[208:211], v[76:79]
	v_mfma_f32_16x16x32_bf16 v[72:75], v[158:161], v[208:211], v[72:75]
	v_mfma_f32_16x16x32_bf16 v[124:127], v[154:157], v[186:189], v[124:127]
	v_mfma_f32_16x16x32_bf16 v[120:123], v[162:165], v[186:189], v[120:123]
	v_mfma_f32_16x16x32_bf16 v[108:111], v[154:157], v[196:199], v[108:111]
	v_mfma_f32_16x16x32_bf16 v[104:107], v[162:165], v[196:199], v[104:107]
	v_mfma_f32_16x16x32_bf16 v[92:95], v[154:157], v[204:207], v[92:95]
	v_mfma_f32_16x16x32_bf16 v[88:91], v[162:165], v[204:207], v[88:91]
	v_mfma_f32_16x16x32_bf16 v[76:79], v[154:157], v[212:215], v[76:79]
	v_mfma_f32_16x16x32_bf16 v[72:75], v[162:165], v[212:215], v[72:75]
	s_setprio 0
	s_setprio 1
	v_mfma_f32_16x16x32_bf16 v[116:119], v[166:169], v[182:185], v[116:119]
	v_mfma_f32_16x16x32_bf16 v[112:115], v[174:177], v[182:185], v[112:115]
	v_mfma_f32_16x16x32_bf16 v[100:103], v[166:169], v[192:195], v[100:103]
	v_mfma_f32_16x16x32_bf16 v[96:99], v[174:177], v[192:195], v[96:99]
	v_mfma_f32_16x16x32_bf16 v[84:87], v[166:169], v[200:203], v[84:87]
	v_mfma_f32_16x16x32_bf16 v[80:83], v[174:177], v[200:203], v[80:83]
	v_mfma_f32_16x16x32_bf16 v[68:71], v[166:169], v[208:211], v[68:71]
	v_mfma_f32_16x16x32_bf16 v[64:67], v[174:177], v[208:211], v[64:67]
	v_mfma_f32_16x16x32_bf16 v[116:119], v[170:173], v[186:189], v[116:119]
	v_mfma_f32_16x16x32_bf16 v[112:115], v[178:181], v[186:189], v[112:115]
	v_mfma_f32_16x16x32_bf16 v[100:103], v[170:173], v[196:199], v[100:103]
	v_mfma_f32_16x16x32_bf16 v[96:99], v[178:181], v[196:199], v[96:99]
	v_mfma_f32_16x16x32_bf16 v[84:87], v[170:173], v[204:207], v[84:87]
	v_mfma_f32_16x16x32_bf16 v[80:83], v[178:181], v[204:207], v[80:83]
	v_mfma_f32_16x16x32_bf16 v[68:71], v[170:173], v[212:215], v[68:71]
	v_mfma_f32_16x16x32_bf16 v[64:67], v[178:181], v[212:215], v[64:67]
	s_setprio 0
	s_barrier
	s_add_i32 s56, s44, s36
	v_lshl_add_u64 v[216:217], s[30:31], 0, v[132:133]
	s_mov_b32 m0, s56
	ds_read_b128 v[182:185], v149 offset:16384
	ds_read_b128 v[186:189], v149 offset:17408
	ds_read_b128 v[192:195], v149 offset:18432
	ds_read_b128 v[196:199], v149 offset:19456
	ds_read_b128 v[200:203], v149 offset:20480
	ds_read_b128 v[204:207], v149 offset:21504
	ds_read_b128 v[208:211], v149 offset:22528
	ds_read_b128 v[212:215], v149 offset:23552
	global_load_lds_dwordx4 v[216:217], off
	s_add_i32 m0, s56, 0x2000
	s_add_u32 s56, s30, 0x80000
	v_lshl_add_u64 v[218:219], s[30:31], 0, v[128:129]
	s_addc_u32 s57, s31, 0
	s_add_i32 s58, s91, s36
	global_load_lds_dwordx4 v[218:219], off
	s_mov_b32 m0, s58
	v_lshl_add_u64 v[222:223], s[34:35], 0, v[130:131]
	global_load_lds_dwordx4 v132, s[56:57]
	s_add_i32 m0, s58, 0x2000
	s_nop 0
	global_load_lds_dwordx4 v128, s[56:57]
	v_lshl_add_u64 v[220:221], s[34:35], 0, v[134:135]
	s_mov_b32 m0, s27
	s_nop 0
	global_load_lds_dwordx4 v[220:221], off
	s_mov_b32 m0, s38
	s_nop 0
	global_load_lds_dwordx4 v[222:223], off
	s_waitcnt vmcnt(8)
	s_waitcnt lgkmcnt(0)
	s_barrier
; #define PG8_STAGE(bufoff, gbase, voff) do { _Pragma("unroll") for (int _i = 0; _i < 2; ++_i) \
;         __builtin_amdgcn_global_load_lds((const unsigned*)((const char*)(gbase) + (voff)[_i]), (LAS unsigned*)(lds + (bufoff) + ldsw + _i * 8192), 16, 0, 0); } while (0)
; #define PG8_LDA(dst, b, h) do { _Pragma("unroll") for (int m = 0; m < 4; ++m) _Pragma("unroll") for (int k = 0; k < 2; ++k) dst[m][k] = *(const LAS bf16x8*)(lds + PG8_SA(b, h) + aoff + m * 2048 + k * 1024); } while (0)
; #define PG8_LDB(dst, b, h) do { _Pragma("unroll") for (int n = 0; n < 2; ++n) _Pragma("unroll") for (int k = 0; k < 2; ++k) dst[n][k] = *(const LAS bf16x8*)(lds + PG8_SB(b, h) + boff + n * 2048 + k * 1024); } while (0)
; #define PG8_WAIT_V(n) asm volatile("s_waitcnt vmcnt(" #n ")" ::: "memory")
; #define PG8_WAIT_L(n) asm volatile("s_waitcnt lgkmcnt(" #n ")" ::: "memory")
; #define PG8_BAR __builtin_amdgcn_s_barrier()
; #define PG8_SCHED __builtin_amdgcn_sched_barrier(0)
; template <class Epi, class Sched, bool F8 = false>
; __device__ __forceinline__ void gemm_phase(LAS unsigned char* lds, const Gemm g, const Sched& S, const Epi& E) {
;     ...
;             PG8_WAIT_V(8); PG8_WAIT_L(0); PG8_BAR; PG8_MMA(1, 0, At, B0); PG8_MMA(1, 1, At, B1); PG8_BAR; PG8_SCHED;
;             PG8_LDB(B0, 1, 0); PG8_LDB(B1, 1, 1); PG8_SCHED; PG8_LDA(At, 1, 0); PG8_STAGE(PG8_SA(0, 1), a2 + hstepA, voffA);
;             PG8_WAIT_V(8); PG8_WAIT_L(0); PG8_BAR; PG8_MMA(0, 0, At, B0); PG8_MMA(0, 1, At, B1); PG8_BAR; PG8_SCHED;
	s_setprio 1
	s_waitcnt lgkmcnt(0)
	v_mfma_f32_16x16x32_bf16 v[60:63], v[150:153], v[182:185], v[60:63]
	v_mfma_f32_16x16x32_bf16 v[56:59], v[158:161], v[182:185], v[56:59]
	v_mfma_f32_16x16x32_bf16 v[44:47], v[150:153], v[192:195], v[44:47]
	v_mfma_f32_16x16x32_bf16 v[40:43], v[158:161], v[192:195], v[40:43]
	v_mfma_f32_16x16x32_bf16 v[28:31], v[150:153], v[200:203], v[28:31]
	v_mfma_f32_16x16x32_bf16 v[24:27], v[158:161], v[200:203], v[24:27]
	v_mfma_f32_16x16x32_bf16 v[12:15], v[150:153], v[208:211], v[12:15]
	v_mfma_f32_16x16x32_bf16 v[8:11], v[158:161], v[208:211], v[8:11]
	v_mfma_f32_16x16x32_bf16 v[60:63], v[154:157], v[186:189], v[60:63]
	v_mfma_f32_16x16x32_bf16 v[56:59], v[162:165], v[186:189], v[56:59]
	v_mfma_f32_16x16x32_bf16 v[44:47], v[154:157], v[196:199], v[44:47]
	v_mfma_f32_16x16x32_bf16 v[40:43], v[162:165], v[196:199], v[40:43]
	v_mfma_f32_16x16x32_bf16 v[28:31], v[154:157], v[204:207], v[28:31]
	v_mfma_f32_16x16x32_bf16 v[24:27], v[162:165], v[204:207], v[24:27]
	v_mfma_f32_16x16x32_bf16 v[12:15], v[154:157], v[212:215], v[12:15]
	v_mfma_f32_16x16x32_bf16 v[8:11], v[162:165], v[212:215], v[8:11]
	s_setprio 0
	s_setprio 1
	v_mfma_f32_16x16x32_bf16 v[52:55], v[166:169], v[182:185], v[52:55]
	v_mfma_f32_16x16x32_bf16 v[48:51], v[174:177], v[182:185], v[48:51]
	v_mfma_f32_16x16x32_bf16 v[36:39], v[166:169], v[192:195], v[36:39]
	v_mfma_f32_16x16x32_bf16 v[32:35], v[174:177], v[192:195], v[32:35]
	v_mfma_f32_16x16x32_bf16 v[20:23], v[166:169], v[200:203], v[20:23]
	v_mfma_f32_16x16x32_bf16 v[16:19], v[174:177], v[200:203], v[16:19]
	v_mfma_f32_16x16x32_bf16 v[4:7], v[166:169], v[208:211], v[4:7]
	v_mfma_f32_16x16x32_bf16 v[0:3], v[174:177], v[208:211], v[0:3]
	v_mfma_f32_16x16x32_bf16 v[52:55], v[170:173], v[186:189], v[52:55]
	v_mfma_f32_16x16x32_bf16 v[48:51], v[178:181], v[186:189], v[48:51]
	v_mfma_f32_16x16x32_bf16 v[36:39], v[170:173], v[196:199], v[36:39]
	v_mfma_f32_16x16x32_bf16 v[32:35], v[178:181], v[196:199], v[32:35]
	v_mfma_f32_16x16x32_bf16 v[20:23], v[170:173], v[204:207], v[20:23]
	v_mfma_f32_16x16x32_bf16 v[16:19], v[178:181], v[204:207], v[16:19]
	v_mfma_f32_16x16x32_bf16 v[4:7], v[170:173], v[212:215], v[4:7]
	v_mfma_f32_16x16x32_bf16 v[0:3], v[178:181], v[212:215], v[0:3]
	s_setprio 0
	s_barrier
	s_add_i32 s56, 0, 0x18000
	s_add_i32 s57, 0, 0x1c000
	v_add_u32_e32 v162, s56, v145
	v_add_u32_e32 v178, s57, v145
	ds_read_b128 v[150:153], v162
	ds_read_b128 v[154:157], v162 offset:1024
	ds_read_b128 v[158:161], v162 offset:2048
	ds_read_b128 v[162:165], v162 offset:3072
	ds_read_b128 v[166:169], v178
	ds_read_b128 v[170:173], v178 offset:1024
	ds_read_b128 v[174:177], v178 offset:2048
	ds_read_b128 v[178:181], v178 offset:3072
	s_add_u32 s34, s34, 0x80000
	s_addc_u32 s35, s35, 0
	s_mov_b32 m0, s39
	ds_read_b128 v[182:185], v149 offset:32768
	ds_read_b128 v[186:189], v149 offset:33792
	ds_read_b128 v[192:195], v149 offset:34816
	ds_read_b128 v[196:199], v149 offset:35840
	ds_read_b128 v[200:203], v149 offset:36864
	ds_read_b128 v[204:207], v149 offset:37888
	ds_read_b128 v[208:211], v149 offset:38912
	ds_read_b128 v[212:215], v149 offset:39936
	global_load_lds_dwordx4 v134, s[34:35]
	s_mov_b32 m0, s40
	s_nop 0
	global_load_lds_dwordx4 v130, s[34:35]
	s_waitcnt vmcnt(8)
	s_waitcnt lgkmcnt(0)
	s_barrier
	s_setprio 1
	s_waitcnt lgkmcnt(0)
	v_mfma_f32_16x16x32_bf16 v[124:127], v[150:153], v[182:185], v[124:127]
	v_mfma_f32_16x16x32_bf16 v[120:123], v[158:161], v[182:185], v[120:123]
	v_mfma_f32_16x16x32_bf16 v[108:111], v[150:153], v[192:195], v[108:111]
	v_mfma_f32_16x16x32_bf16 v[104:107], v[158:161], v[192:195], v[104:107]
	v_mfma_f32_16x16x32_bf16 v[92:95], v[150:153], v[200:203], v[92:95]
	v_mfma_f32_16x16x32_bf16 v[88:91], v[158:161], v[200:203], v[88:91]
	v_mfma_f32_16x16x32_bf16 v[76:79], v[150:153], v[208:211], v[76:79]
	v_mfma_f32_16x16x32_bf16 v[72:75], v[158:161], v[208:211], v[72:75]
	v_mfma_f32_16x16x32_bf16 v[124:127], v[154:157], v[186:189], v[124:127]
	v_mfma_f32_16x16x32_bf16 v[120:123], v[162:165], v[186:189], v[120:123]
	v_mfma_f32_16x16x32_bf16 v[108:111], v[154:157], v[196:199], v[108:111]
	v_mfma_f32_16x16x32_bf16 v[104:107], v[162:165], v[196:199], v[104:107]
	v_mfma_f32_16x16x32_bf16 v[92:95], v[154:157], v[204:207], v[92:95]
	v_mfma_f32_16x16x32_bf16 v[88:91], v[162:165], v[204:207], v[88:91]
	v_mfma_f32_16x16x32_bf16 v[76:79], v[154:157], v[212:215], v[76:79]
	v_mfma_f32_16x16x32_bf16 v[72:75], v[162:165], v[212:215], v[72:75]
	s_setprio 0
	s_setprio 1
	v_mfma_f32_16x16x32_bf16 v[116:119], v[166:169], v[182:185], v[116:119]
	v_mfma_f32_16x16x32_bf16 v[112:115], v[174:177], v[182:185], v[112:115]
	v_mfma_f32_16x16x32_bf16 v[100:103], v[166:169], v[192:195], v[100:103]
	v_mfma_f32_16x16x32_bf16 v[96:99], v[174:177], v[192:195], v[96:99]
	v_mfma_f32_16x16x32_bf16 v[84:87], v[166:169], v[200:203], v[84:87]
	v_mfma_f32_16x16x32_bf16 v[80:83], v[174:177], v[200:203], v[80:83]
	v_mfma_f32_16x16x32_bf16 v[68:71], v[166:169], v[208:211], v[68:71]
	v_mfma_f32_16x16x32_bf16 v[64:67], v[174:177], v[208:211], v[64:67]
	v_mfma_f32_16x16x32_bf16 v[116:119], v[170:173], v[186:189], v[116:119]
	v_mfma_f32_16x16x32_bf16 v[112:115], v[178:181], v[186:189], v[112:115]
	v_mfma_f32_16x16x32_bf16 v[100:103], v[170:173], v[196:199], v[100:103]
	v_mfma_f32_16x16x32_bf16 v[96:99], v[178:181], v[196:199], v[96:99]
	v_mfma_f32_16x16x32_bf16 v[84:87], v[170:173], v[204:207], v[84:87]
	v_mfma_f32_16x16x32_bf16 v[80:83], v[178:181], v[204:207], v[80:83]
	v_mfma_f32_16x16x32_bf16 v[68:71], v[170:173], v[212:215], v[68:71]
	v_mfma_f32_16x16x32_bf16 v[64:67], v[178:181], v[212:215], v[64:67]
	s_setprio 0
	s_barrier
; #define PG8_STAGE(bufoff, gbase, voff) do { _Pragma("unroll") for (int _i = 0; _i < 2; ++_i) \
;         __builtin_amdgcn_global_load_lds((const unsigned*)((const char*)(gbase) + (voff)[_i]), (LAS unsigned*)(lds + (bufoff) + ldsw + _i * 8192), 16, 0, 0); } while (0)
; #define PG8_LDA(dst, b, h) do { _Pragma("unroll") for (int m = 0; m < 4; ++m) _Pragma("unroll") for (int k = 0; k < 2; ++k) dst[m][k] = *(const LAS bf16x8*)(lds + PG8_SA(b, h) + aoff + m * 2048 + k * 1024); } while (0)
; #define PG8_WAIT_V(n) asm volatile("s_waitcnt vmcnt(" #n ")" ::: "memory")
; #define PG8_WAIT_L(n) asm volatile("s_waitcnt lgkmcnt(" #n ")" ::: "memory")
; #define PG8_BAR __builtin_amdgcn_s_barrier()
; #define PG8_SCHED __builtin_amdgcn_sched_barrier(0)
; template <class Epi, class Sched, bool F8 = false>
; __device__ __forceinline__ void gemm_phase(LAS unsigned char* lds, const Gemm g, const Sched& S, const Epi& E) {
;     ...
;             PG8_LDA(At, 1, 1); PG8_STAGE(PG8_SB(1, 0), b3, voffB); PG8_STAGE(PG8_SB(1, 1), b3 + hstepB, voffB); PG8_STAGE(PG8_SA(1, 0), a3, voffA);
;             PG8_WAIT_V(8); PG8_WAIT_L(0); PG8_BAR; PG8_MMA(1, 0, At, B0); PG8_MMA(1, 1, At, B1); PG8_BAR; PG8_SCHED;
;         }
;         if (wr == 0) PG8_BAR;
	s_add_i32 s34, s56, s36
	v_lshl_add_u64 v[216:217], v[216:217], 0, s[12:13]
	s_mov_b32 m0, s34
	ds_read_b128 v[182:185], v149 offset:49152
	ds_read_b128 v[186:189], v149 offset:50176
	ds_read_b128 v[192:195], v149 offset:51200
	ds_read_b128 v[196:199], v149 offset:52224
	ds_read_b128 v[200:203], v149 offset:53248
	ds_read_b128 v[204:207], v149 offset:54272
	ds_read_b128 v[208:211], v149 offset:55296
	ds_read_b128 v[212:215], v149 offset:56320
	global_load_lds_dwordx4 v[216:217], off
	s_add_i32 m0, s34, 0x2000
	s_add_u32 s30, s30, 0x80080
	v_lshl_add_u64 v[216:217], v[218:219], 0, s[12:13]
	s_addc_u32 s31, s31, 0
	s_add_i32 s34, s57, s36
	global_load_lds_dwordx4 v[216:217], off
	s_mov_b32 m0, s34
	s_nop 0
	global_load_lds_dwordx4 v132, s[30:31]
	s_add_i32 m0, s34, 0x2000
	s_nop 0
	global_load_lds_dwordx4 v128, s[30:31]
	v_lshl_add_u64 v[216:217], v[220:221], 0, s[12:13]
	s_mov_b32 m0, s42
	s_nop 0
	global_load_lds_dwordx4 v[216:217], off
	v_lshl_add_u64 v[216:217], v[222:223], 0, s[12:13]
	s_mov_b32 m0, s43
	s_nop 0
	global_load_lds_dwordx4 v[216:217], off
	s_waitcnt vmcnt(8)
	s_waitcnt lgkmcnt(0)
	s_barrier
	s_setprio 1
	s_waitcnt lgkmcnt(0)
	v_mfma_f32_16x16x32_bf16 v[60:63], v[150:153], v[182:185], v[60:63]
	v_mfma_f32_16x16x32_bf16 v[56:59], v[158:161], v[182:185], v[56:59]
	v_mfma_f32_16x16x32_bf16 v[44:47], v[150:153], v[192:195], v[44:47]
	v_mfma_f32_16x16x32_bf16 v[40:43], v[158:161], v[192:195], v[40:43]
	v_mfma_f32_16x16x32_bf16 v[28:31], v[150:153], v[200:203], v[28:31]
	v_mfma_f32_16x16x32_bf16 v[24:27], v[158:161], v[200:203], v[24:27]
	v_mfma_f32_16x16x32_bf16 v[12:15], v[150:153], v[208:211], v[12:15]
	v_mfma_f32_16x16x32_bf16 v[8:11], v[158:161], v[208:211], v[8:11]
	v_mfma_f32_16x16x32_bf16 v[60:63], v[154:157], v[186:189], v[60:63]
	v_mfma_f32_16x16x32_bf16 v[56:59], v[162:165], v[186:189], v[56:59]
	v_mfma_f32_16x16x32_bf16 v[44:47], v[154:157], v[196:199], v[44:47]
	v_mfma_f32_16x16x32_bf16 v[40:43], v[162:165], v[196:199], v[40:43]
	v_mfma_f32_16x16x32_bf16 v[28:31], v[154:157], v[204:207], v[28:31]
	v_mfma_f32_16x16x32_bf16 v[24:27], v[162:165], v[204:207], v[24:27]
	v_mfma_f32_16x16x32_bf16 v[12:15], v[154:157], v[212:215], v[12:15]
	v_mfma_f32_16x16x32_bf16 v[8:11], v[162:165], v[212:215], v[8:11]
	s_setprio 0
	s_setprio 1
	v_mfma_f32_16x16x32_bf16 v[52:55], v[166:169], v[182:185], v[52:55]
	v_mfma_f32_16x16x32_bf16 v[48:51], v[174:177], v[182:185], v[48:51]
	v_mfma_f32_16x16x32_bf16 v[36:39], v[166:169], v[192:195], v[36:39]
	v_mfma_f32_16x16x32_bf16 v[32:35], v[174:177], v[192:195], v[32:35]
	v_mfma_f32_16x16x32_bf16 v[20:23], v[166:169], v[200:203], v[20:23]
	v_mfma_f32_16x16x32_bf16 v[16:19], v[174:177], v[200:203], v[16:19]
	v_mfma_f32_16x16x32_bf16 v[4:7], v[166:169], v[208:211], v[4:7]
	v_mfma_f32_16x16x32_bf16 v[0:3], v[174:177], v[208:211], v[0:3]
	v_mfma_f32_16x16x32_bf16 v[52:55], v[170:173], v[186:189], v[52:55]
	v_mfma_f32_16x16x32_bf16 v[48:51], v[178:181], v[186:189], v[48:51]
	v_mfma_f32_16x16x32_bf16 v[36:39], v[170:173], v[196:199], v[36:39]
	v_mfma_f32_16x16x32_bf16 v[32:35], v[178:181], v[196:199], v[32:35]
	v_mfma_f32_16x16x32_bf16 v[20:23], v[170:173], v[204:207], v[20:23]
	v_mfma_f32_16x16x32_bf16 v[16:19], v[178:181], v[204:207], v[16:19]
	v_mfma_f32_16x16x32_bf16 v[4:7], v[170:173], v[212:215], v[4:7]
	v_mfma_f32_16x16x32_bf16 v[0:3], v[178:181], v[212:215], v[0:3]
	s_setprio 0
	s_barrier
	s_add_i32 s53, s53, 2
	s_add_u32 s28, s28, 0x100
	s_addc_u32 s29, s29, 0
	s_add_u32 s50, s50, 0x100
	s_addc_u32 s51, s51, 0
	s_cmp_gt_u32 s53, 29
	s_cbranch_scc0 .LBB0_954
	s_and_b64 vcc, exec, s[14:15]
	s_cbranch_vccz .LBB0_957
	s_barrier

; #define PG8_STAGE(bufoff, gbase, voff) do { _Pragma("unroll") for (int _i = 0; _i < 2; ++_i) \
;         __builtin_amdgcn_global_load_lds((const unsigned*)((const char*)(gbase) + (voff)[_i]), (LAS unsigned*)(lds + (bufoff) + ldsw + _i * 8192), 16, 0, 0); } while (0)
; #define PG8_LDA(dst, b, h) do { _Pragma("unroll") for (int m = 0; m < 4; ++m) _Pragma("unroll") for (int k = 0; k < 2; ++k) dst[m][k] = *(const LAS bf16x8*)(lds + PG8_SA(b, h) + aoff + m * 2048 + k * 1024); } while (0)
; #define PG8_LDB(dst, b, h) do { _Pragma("unroll") for (int n = 0; n < 2; ++n) _Pragma("unroll") for (int k = 0; k < 2; ++k) dst[n][k] = *(const LAS bf16x8*)(lds + PG8_SB(b, h) + boff + n * 2048 + k * 1024); } while (0)
; #define PG8_WAIT_V(n) asm volatile("s_waitcnt vmcnt(" #n ")" ::: "memory")
; #define PG8_WAIT_L(n) asm volatile("s_waitcnt lgkmcnt(" #n ")" ::: "memory")
; #define PG8_BAR __builtin_amdgcn_s_barrier()
; #define PG8_SCHED __builtin_amdgcn_sched_barrier(0)
; template <class Epi, class Sched, bool F8 = false>
; __device__ __forceinline__ void gemm_phase(LAS unsigned char* lds, const Gemm g, const Sched& S, const Epi& E) {
;     ...
;         for (int t = 0; t < nt; t += 2) {
;             const bool last = (t == nt - 2);
;             const char* a1 = cA + (size_t)(t + 1) * kstep;
;             const char* a2 = last ? nA : cA + (size_t)(t + 2) * kstep; const char* b2 = last ? nB : cB + (size_t)(t + 2) * kstep;
;             const char* a3 = a2 + kstep; const char* b3 = b2 + kstep;
;             PG8_LDB(B0, 0, 0); PG8_LDB(B1, 0, 1); PG8_SCHED; PG8_LDA(At, 0, 0); PG8_STAGE(PG8_SA(1, 1), a1 + hstepA, voffA);
;             PG8_WAIT_V(8); PG8_WAIT_L(0); PG8_BAR; PG8_MMA(0, 0, At, B0); PG8_MMA(0, 1, At, B1); PG8_BAR; PG8_SCHED;
;             PG8_LDA(At, 0, 1); PG8_STAGE(PG8_SB(0, 0), b2, voffB); PG8_STAGE(PG8_SB(0, 1), b2 + hstepB, voffB); PG8_STAGE(PG8_SA(0, 0), a2, voffA);
;             PG8_WAIT_V(8); PG8_WAIT_L(0); PG8_BAR; PG8_MMA(1, 0, At, B0); PG8_MMA(1, 1, At, B1); PG8_BAR; PG8_SCHED;
.LBB0_1030:
	ds_read_b128 v[144:147], v183
	ds_read_b128 v[148:151], v183 offset:1024
	ds_read_b128 v[152:155], v183 offset:2048
	ds_read_b128 v[156:159], v183 offset:3072
	ds_read_b128 v[160:163], v184
	ds_read_b128 v[164:167], v184 offset:1024
	ds_read_b128 v[168:171], v184 offset:2048
	ds_read_b128 v[172:175], v184 offset:3072
	s_add_u32 s28, s26, 0x100
	s_addc_u32 s29, s27, 0
	s_cmpk_eq_i32 s53, 0x54
	s_cselect_b32 s35, s9, s29
	s_cselect_b32 s34, s8, s28
	s_cselect_b32 s31, s25, s51
	s_cselect_b32 s30, s24, s50
	s_add_i32 m0, s37, 0xc000
	ds_read_b128 v[176:179], v185
	ds_read_b128 v[186:189], v185 offset:1024
	ds_read_b128 v[192:195], v185 offset:2048
	ds_read_b128 v[196:199], v185 offset:3072
	ds_read_b128 v[200:203], v185 offset:4096
	ds_read_b128 v[204:207], v185 offset:5120
	ds_read_b128 v[208:211], v185 offset:6144
	ds_read_b128 v[212:215], v185 offset:7168
	global_load_lds_dwordx4 v136, s[26:27]
	s_add_i32 m0, s37, 0xe000
	s_nop 0
	global_load_lds_dwordx4 v138, s[26:27]
	s_waitcnt vmcnt(8)
	s_waitcnt lgkmcnt(0)
	s_barrier
	s_setprio 1
	s_waitcnt lgkmcnt(0)
	v_mfma_f32_16x16x32_bf16 v[124:127], v[144:147], v[176:179], v[124:127]
	v_mfma_f32_16x16x32_bf16 v[120:123], v[152:155], v[176:179], v[120:123]
	v_mfma_f32_16x16x32_bf16 v[108:111], v[144:147], v[192:195], v[108:111]
	v_mfma_f32_16x16x32_bf16 v[104:107], v[152:155], v[192:195], v[104:107]
	v_mfma_f32_16x16x32_bf16 v[92:95], v[144:147], v[200:203], v[92:95]
	v_mfma_f32_16x16x32_bf16 v[88:91], v[152:155], v[200:203], v[88:91]
	v_mfma_f32_16x16x32_bf16 v[76:79], v[144:147], v[208:211], v[76:79]
	v_mfma_f32_16x16x32_bf16 v[72:75], v[152:155], v[208:211], v[72:75]
	v_mfma_f32_16x16x32_bf16 v[124:127], v[148:151], v[186:189], v[124:127]
	v_mfma_f32_16x16x32_bf16 v[120:123], v[156:159], v[186:189], v[120:123]
	v_mfma_f32_16x16x32_bf16 v[108:111], v[148:151], v[196:199], v[108:111]
	v_mfma_f32_16x16x32_bf16 v[104:107], v[156:159], v[196:199], v[104:107]
	v_mfma_f32_16x16x32_bf16 v[92:95], v[148:151], v[204:207], v[92:95]
	v_mfma_f32_16x16x32_bf16 v[88:91], v[156:159], v[204:207], v[88:91]
	v_mfma_f32_16x16x32_bf16 v[76:79], v[148:151], v[212:215], v[76:79]
	v_mfma_f32_16x16x32_bf16 v[72:75], v[156:159], v[212:215], v[72:75]
	s_setprio 0
	s_setprio 1
	v_mfma_f32_16x16x32_bf16 v[116:119], v[160:163], v[176:179], v[116:119]
	v_mfma_f32_16x16x32_bf16 v[112:115], v[168:171], v[176:179], v[112:115]
	v_mfma_f32_16x16x32_bf16 v[100:103], v[160:163], v[192:195], v[100:103]
	v_mfma_f32_16x16x32_bf16 v[96:99], v[168:171], v[192:195], v[96:99]
	v_mfma_f32_16x16x32_bf16 v[84:87], v[160:163], v[200:203], v[84:87]
	v_mfma_f32_16x16x32_bf16 v[80:83], v[168:171], v[200:203], v[80:83]
	v_mfma_f32_16x16x32_bf16 v[68:71], v[160:163], v[208:211], v[68:71]
	v_mfma_f32_16x16x32_bf16 v[64:67], v[168:171], v[208:211], v[64:67]
	v_mfma_f32_16x16x32_bf16 v[116:119], v[164:167], v[186:189], v[116:119]
	v_mfma_f32_16x16x32_bf16 v[112:115], v[172:175], v[186:189], v[112:115]
	v_mfma_f32_16x16x32_bf16 v[100:103], v[164:167], v[196:199], v[100:103]
	v_mfma_f32_16x16x32_bf16 v[96:99], v[172:175], v[196:199], v[96:99]
	v_mfma_f32_16x16x32_bf16 v[84:87], v[164:167], v[204:207], v[84:87]
	v_mfma_f32_16x16x32_bf16 v[80:83], v[172:175], v[204:207], v[80:83]
	v_mfma_f32_16x16x32_bf16 v[68:71], v[164:167], v[212:215], v[68:71]
	v_mfma_f32_16x16x32_bf16 v[64:67], v[172:175], v[212:215], v[64:67]
	s_setprio 0
	s_barrier
	s_add_i32 s26, s44, s23
	v_lshl_add_u64 v[216:217], s[30:31], 0, v[132:133]
	s_mov_b32 m0, s26
	ds_read_b128 v[176:179], v185 offset:16384
	ds_read_b128 v[186:189], v185 offset:17408
	ds_read_b128 v[192:195], v185 offset:18432
	ds_read_b128 v[196:199], v185 offset:19456
	ds_read_b128 v[200:203], v185 offset:20480
	ds_read_b128 v[204:207], v185 offset:21504
	ds_read_b128 v[208:211], v185 offset:22528
	ds_read_b128 v[212:215], v185 offset:23552
	global_load_lds_dwordx4 v[216:217], off
	s_add_i32 m0, s26, 0x2000
	s_add_u32 s26, s30, 0x160000
	v_lshl_add_u64 v[218:219], s[30:31], 0, v[128:129]
	s_addc_u32 s27, s31, 0
	s_add_i32 s56, s91, s23
	global_load_lds_dwordx4 v[218:219], off
	s_mov_b32 m0, s56
	v_lshl_add_u64 v[222:223], s[34:35], 0, v[130:131]
	global_load_lds_dwordx4 v132, s[26:27]
	s_add_i32 m0, s56, 0x2000
	s_nop 0
	global_load_lds_dwordx4 v128, s[26:27]
	v_lshl_add_u64 v[220:221], s[34:35], 0, v[134:135]
	s_mov_b32 m0, s37
	s_nop 0
	global_load_lds_dwordx4 v[220:221], off
	s_mov_b32 m0, s38
	s_nop 0
	global_load_lds_dwordx4 v[222:223], off
	s_waitcnt vmcnt(8)
	s_waitcnt lgkmcnt(0)
	s_barrier
; #define PG8_STAGE(bufoff, gbase, voff) do { _Pragma("unroll") for (int _i = 0; _i < 2; ++_i) \
;         __builtin_amdgcn_global_load_lds((const unsigned*)((const char*)(gbase) + (voff)[_i]), (LAS unsigned*)(lds + (bufoff) + ldsw + _i * 8192), 16, 0, 0); } while (0)
; #define PG8_LDA(dst, b, h) do { _Pragma("unroll") for (int m = 0; m < 4; ++m) _Pragma("unroll") for (int k = 0; k < 2; ++k) dst[m][k] = *(const LAS bf16x8*)(lds + PG8_SA(b, h) + aoff + m * 2048 + k * 1024); } while (0)
; #define PG8_LDB(dst, b, h) do { _Pragma("unroll") for (int n = 0; n < 2; ++n) _Pragma("unroll") for (int k = 0; k < 2; ++k) dst[n][k] = *(const LAS bf16x8*)(lds + PG8_SB(b, h) + boff + n * 2048 + k * 1024); } while (0)
; #define PG8_WAIT_V(n) asm volatile("s_waitcnt vmcnt(" #n ")" ::: "memory")
; #define PG8_WAIT_L(n) asm volatile("s_waitcnt lgkmcnt(" #n ")" ::: "memory")
; #define PG8_BAR __builtin_amdgcn_s_barrier()
; #define PG8_SCHED __builtin_amdgcn_sched_barrier(0)
; template <class Epi, class Sched, bool F8 = false>
; __device__ __forceinline__ void gemm_phase(LAS unsigned char* lds, const Gemm g, const Sched& S, const Epi& E) {
;     ...
;             PG8_WAIT_V(8); PG8_WAIT_L(0); PG8_BAR; PG8_MMA(1, 0, At, B0); PG8_MMA(1, 1, At, B1); PG8_BAR; PG8_SCHED;
;             PG8_LDB(B0, 1, 0); PG8_LDB(B1, 1, 1); PG8_SCHED; PG8_LDA(At, 1, 0); PG8_STAGE(PG8_SA(0, 1), a2 + hstepA, voffA);
;             PG8_WAIT_V(8); PG8_WAIT_L(0); PG8_BAR; PG8_MMA(0, 0, At, B0); PG8_MMA(0, 1, At, B1); PG8_BAR; PG8_SCHED;
	s_setprio 1
	s_waitcnt lgkmcnt(0)
	v_mfma_f32_16x16x32_bf16 v[60:63], v[144:147], v[176:179], v[60:63]
	v_mfma_f32_16x16x32_bf16 v[56:59], v[152:155], v[176:179], v[56:59]
	v_mfma_f32_16x16x32_bf16 v[44:47], v[144:147], v[192:195], v[44:47]
	v_mfma_f32_16x16x32_bf16 v[40:43], v[152:155], v[192:195], v[40:43]
	v_mfma_f32_16x16x32_bf16 v[28:31], v[144:147], v[200:203], v[28:31]
	v_mfma_f32_16x16x32_bf16 v[24:27], v[152:155], v[200:203], v[24:27]
	v_mfma_f32_16x16x32_bf16 v[12:15], v[144:147], v[208:211], v[12:15]
	v_mfma_f32_16x16x32_bf16 v[8:11], v[152:155], v[208:211], v[8:11]
	v_mfma_f32_16x16x32_bf16 v[60:63], v[148:151], v[186:189], v[60:63]
	v_mfma_f32_16x16x32_bf16 v[56:59], v[156:159], v[186:189], v[56:59]
	v_mfma_f32_16x16x32_bf16 v[44:47], v[148:151], v[196:199], v[44:47]
	v_mfma_f32_16x16x32_bf16 v[40:43], v[156:159], v[196:199], v[40:43]
	v_mfma_f32_16x16x32_bf16 v[28:31], v[148:151], v[204:207], v[28:31]
	v_mfma_f32_16x16x32_bf16 v[24:27], v[156:159], v[204:207], v[24:27]
	v_mfma_f32_16x16x32_bf16 v[12:15], v[148:151], v[212:215], v[12:15]
	v_mfma_f32_16x16x32_bf16 v[8:11], v[156:159], v[212:215], v[8:11]
	s_setprio 0
	s_setprio 1
	v_mfma_f32_16x16x32_bf16 v[52:55], v[160:163], v[176:179], v[52:55]
	v_mfma_f32_16x16x32_bf16 v[48:51], v[168:171], v[176:179], v[48:51]
	v_mfma_f32_16x16x32_bf16 v[36:39], v[160:163], v[192:195], v[36:39]
	v_mfma_f32_16x16x32_bf16 v[32:35], v[168:171], v[192:195], v[32:35]
	v_mfma_f32_16x16x32_bf16 v[20:23], v[160:163], v[200:203], v[20:23]
	v_mfma_f32_16x16x32_bf16 v[16:19], v[168:171], v[200:203], v[16:19]
	v_mfma_f32_16x16x32_bf16 v[4:7], v[160:163], v[208:211], v[4:7]
	v_mfma_f32_16x16x32_bf16 v[0:3], v[168:171], v[208:211], v[0:3]
	v_mfma_f32_16x16x32_bf16 v[52:55], v[164:167], v[186:189], v[52:55]
	v_mfma_f32_16x16x32_bf16 v[48:51], v[172:175], v[186:189], v[48:51]
	v_mfma_f32_16x16x32_bf16 v[36:39], v[164:167], v[196:199], v[36:39]
	v_mfma_f32_16x16x32_bf16 v[32:35], v[172:175], v[196:199], v[32:35]
	v_mfma_f32_16x16x32_bf16 v[20:23], v[164:167], v[204:207], v[20:23]
	v_mfma_f32_16x16x32_bf16 v[16:19], v[172:175], v[204:207], v[16:19]
	v_mfma_f32_16x16x32_bf16 v[4:7], v[164:167], v[212:215], v[4:7]
	v_mfma_f32_16x16x32_bf16 v[0:3], v[172:175], v[212:215], v[0:3]
	s_setprio 0
	s_barrier
	s_add_i32 s56, 0, 0x18000
	s_add_i32 s57, 0, 0x1c000
	v_add_u32_e32 v156, s56, v181
	v_add_u32_e32 v172, s57, v181
	ds_read_b128 v[144:147], v156
	ds_read_b128 v[148:151], v156 offset:1024
	ds_read_b128 v[152:155], v156 offset:2048
	ds_read_b128 v[156:159], v156 offset:3072
	ds_read_b128 v[160:163], v172
	ds_read_b128 v[164:167], v172 offset:1024
	ds_read_b128 v[168:171], v172 offset:2048
	ds_read_b128 v[172:175], v172 offset:3072
	s_add_u32 s26, s34, 0x160000
	s_addc_u32 s27, s35, 0
	s_mov_b32 m0, s39
	ds_read_b128 v[176:179], v185 offset:32768
	ds_read_b128 v[186:189], v185 offset:33792
	ds_read_b128 v[192:195], v185 offset:34816
	ds_read_b128 v[196:199], v185 offset:35840
	ds_read_b128 v[200:203], v185 offset:36864
	ds_read_b128 v[204:207], v185 offset:37888
	ds_read_b128 v[208:211], v185 offset:38912
	ds_read_b128 v[212:215], v185 offset:39936
	global_load_lds_dwordx4 v134, s[26:27]
	s_mov_b32 m0, s40
	s_nop 0
	global_load_lds_dwordx4 v130, s[26:27]
	s_waitcnt vmcnt(8)
	s_waitcnt lgkmcnt(0)
	s_barrier
	s_setprio 1
	s_waitcnt lgkmcnt(0)
	v_mfma_f32_16x16x32_bf16 v[124:127], v[144:147], v[176:179], v[124:127]
	v_mfma_f32_16x16x32_bf16 v[120:123], v[152:155], v[176:179], v[120:123]
	v_mfma_f32_16x16x32_bf16 v[108:111], v[144:147], v[192:195], v[108:111]
	v_mfma_f32_16x16x32_bf16 v[104:107], v[152:155], v[192:195], v[104:107]
	v_mfma_f32_16x16x32_bf16 v[92:95], v[144:147], v[200:203], v[92:95]
	v_mfma_f32_16x16x32_bf16 v[88:91], v[152:155], v[200:203], v[88:91]
	v_mfma_f32_16x16x32_bf16 v[76:79], v[144:147], v[208:211], v[76:79]
	v_mfma_f32_16x16x32_bf16 v[72:75], v[152:155], v[208:211], v[72:75]
	v_mfma_f32_16x16x32_bf16 v[124:127], v[148:151], v[186:189], v[124:127]
	v_mfma_f32_16x16x32_bf16 v[120:123], v[156:159], v[186:189], v[120:123]
	v_mfma_f32_16x16x32_bf16 v[108:111], v[148:151], v[196:199], v[108:111]
	v_mfma_f32_16x16x32_bf16 v[104:107], v[156:159], v[196:199], v[104:107]
	v_mfma_f32_16x16x32_bf16 v[92:95], v[148:151], v[204:207], v[92:95]
	v_mfma_f32_16x16x32_bf16 v[88:91], v[156:159], v[204:207], v[88:91]
	v_mfma_f32_16x16x32_bf16 v[76:79], v[148:151], v[212:215], v[76:79]
	v_mfma_f32_16x16x32_bf16 v[72:75], v[156:159], v[212:215], v[72:75]
	s_setprio 0
	s_setprio 1
	v_mfma_f32_16x16x32_bf16 v[116:119], v[160:163], v[176:179], v[116:119]
	v_mfma_f32_16x16x32_bf16 v[112:115], v[168:171], v[176:179], v[112:115]
	v_mfma_f32_16x16x32_bf16 v[100:103], v[160:163], v[192:195], v[100:103]
	v_mfma_f32_16x16x32_bf16 v[96:99], v[168:171], v[192:195], v[96:99]
	v_mfma_f32_16x16x32_bf16 v[84:87], v[160:163], v[200:203], v[84:87]
	v_mfma_f32_16x16x32_bf16 v[80:83], v[168:171], v[200:203], v[80:83]
	v_mfma_f32_16x16x32_bf16 v[68:71], v[160:163], v[208:211], v[68:71]
	v_mfma_f32_16x16x32_bf16 v[64:67], v[168:171], v[208:211], v[64:67]
	v_mfma_f32_16x16x32_bf16 v[116:119], v[164:167], v[186:189], v[116:119]
	v_mfma_f32_16x16x32_bf16 v[112:115], v[172:175], v[186:189], v[112:115]
	v_mfma_f32_16x16x32_bf16 v[100:103], v[164:167], v[196:199], v[100:103]
	v_mfma_f32_16x16x32_bf16 v[96:99], v[172:175], v[196:199], v[96:99]
	v_mfma_f32_16x16x32_bf16 v[84:87], v[164:167], v[204:207], v[84:87]
	v_mfma_f32_16x16x32_bf16 v[80:83], v[172:175], v[204:207], v[80:83]
	v_mfma_f32_16x16x32_bf16 v[68:71], v[164:167], v[212:215], v[68:71]
	v_mfma_f32_16x16x32_bf16 v[64:67], v[172:175], v[212:215], v[64:67]
	s_setprio 0
	s_barrier
; #define PG8_STAGE(bufoff, gbase, voff) do { _Pragma("unroll") for (int _i = 0; _i < 2; ++_i) \
;         __builtin_amdgcn_global_load_lds((const unsigned*)((const char*)(gbase) + (voff)[_i]), (LAS unsigned*)(lds + (bufoff) + ldsw + _i * 8192), 16, 0, 0); } while (0)
; #define PG8_LDA(dst, b, h) do { _Pragma("unroll") for (int m = 0; m < 4; ++m) _Pragma("unroll") for (int k = 0; k < 2; ++k) dst[m][k] = *(const LAS bf16x8*)(lds + PG8_SA(b, h) + aoff + m * 2048 + k * 1024); } while (0)
; #define PG8_WAIT_V(n) asm volatile("s_waitcnt vmcnt(" #n ")" ::: "memory")
; #define PG8_WAIT_L(n) asm volatile("s_waitcnt lgkmcnt(" #n ")" ::: "memory")
; #define PG8_BAR __builtin_amdgcn_s_barrier()
; #define PG8_SCHED __builtin_amdgcn_sched_barrier(0)
; template <class Epi, class Sched, bool F8 = false>
; __device__ __forceinline__ void gemm_phase(LAS unsigned char* lds, const Gemm g, const Sched& S, const Epi& E) {
;     ...
;             PG8_LDA(At, 1, 1); PG8_STAGE(PG8_SB(1, 0), b3, voffB); PG8_STAGE(PG8_SB(1, 1), b3 + hstepB, voffB); PG8_STAGE(PG8_SA(1, 0), a3, voffA);
;             PG8_WAIT_V(8); PG8_WAIT_L(0); PG8_BAR; PG8_MMA(1, 0, At, B0); PG8_MMA(1, 1, At, B1); PG8_BAR; PG8_SCHED;
;         }
;         if (wr == 0) PG8_BAR;
	s_add_i32 s26, s56, s23
	v_lshl_add_u64 v[216:217], v[216:217], 0, s[18:19]
	s_mov_b32 m0, s26
	ds_read_b128 v[176:179], v185 offset:49152
	ds_read_b128 v[186:189], v185 offset:50176
	ds_read_b128 v[192:195], v185 offset:51200
	ds_read_b128 v[196:199], v185 offset:52224
	ds_read_b128 v[200:203], v185 offset:53248
	ds_read_b128 v[204:207], v185 offset:54272
	ds_read_b128 v[208:211], v185 offset:55296
	ds_read_b128 v[212:215], v185 offset:56320
	global_load_lds_dwordx4 v[216:217], off
	s_add_i32 m0, s26, 0x2000
	s_add_u32 s26, s30, 0x160080
	v_lshl_add_u64 v[216:217], v[218:219], 0, s[18:19]
	s_addc_u32 s27, s31, 0
	s_add_i32 s30, s57, s23
	global_load_lds_dwordx4 v[216:217], off
	s_mov_b32 m0, s30
	s_nop 0
	global_load_lds_dwordx4 v132, s[26:27]
	s_add_i32 m0, s30, 0x2000
	s_nop 0
	global_load_lds_dwordx4 v128, s[26:27]
	v_lshl_add_u64 v[216:217], v[220:221], 0, s[18:19]
	s_mov_b32 m0, s42
	s_nop 0
	global_load_lds_dwordx4 v[216:217], off
	v_lshl_add_u64 v[216:217], v[222:223], 0, s[18:19]
	s_mov_b32 m0, s43
	s_nop 0
	global_load_lds_dwordx4 v[216:217], off
	s_waitcnt vmcnt(8)
	s_waitcnt lgkmcnt(0)
	s_barrier
	s_setprio 1
	s_waitcnt lgkmcnt(0)
	v_mfma_f32_16x16x32_bf16 v[60:63], v[144:147], v[176:179], v[60:63]
	v_mfma_f32_16x16x32_bf16 v[56:59], v[152:155], v[176:179], v[56:59]
	v_mfma_f32_16x16x32_bf16 v[44:47], v[144:147], v[192:195], v[44:47]
	v_mfma_f32_16x16x32_bf16 v[40:43], v[152:155], v[192:195], v[40:43]
	v_mfma_f32_16x16x32_bf16 v[28:31], v[144:147], v[200:203], v[28:31]
	v_mfma_f32_16x16x32_bf16 v[24:27], v[152:155], v[200:203], v[24:27]
	v_mfma_f32_16x16x32_bf16 v[12:15], v[144:147], v[208:211], v[12:15]
	v_mfma_f32_16x16x32_bf16 v[8:11], v[152:155], v[208:211], v[8:11]
	v_mfma_f32_16x16x32_bf16 v[60:63], v[148:151], v[186:189], v[60:63]
	v_mfma_f32_16x16x32_bf16 v[56:59], v[156:159], v[186:189], v[56:59]
	v_mfma_f32_16x16x32_bf16 v[44:47], v[148:151], v[196:199], v[44:47]
	v_mfma_f32_16x16x32_bf16 v[40:43], v[156:159], v[196:199], v[40:43]
	v_mfma_f32_16x16x32_bf16 v[28:31], v[148:151], v[204:207], v[28:31]
	v_mfma_f32_16x16x32_bf16 v[24:27], v[156:159], v[204:207], v[24:27]
	v_mfma_f32_16x16x32_bf16 v[12:15], v[148:151], v[212:215], v[12:15]
	v_mfma_f32_16x16x32_bf16 v[8:11], v[156:159], v[212:215], v[8:11]
	s_setprio 0
	s_setprio 1
	v_mfma_f32_16x16x32_bf16 v[52:55], v[160:163], v[176:179], v[52:55]
	v_mfma_f32_16x16x32_bf16 v[48:51], v[168:171], v[176:179], v[48:51]
	v_mfma_f32_16x16x32_bf16 v[36:39], v[160:163], v[192:195], v[36:39]
	v_mfma_f32_16x16x32_bf16 v[32:35], v[168:171], v[192:195], v[32:35]
	v_mfma_f32_16x16x32_bf16 v[20:23], v[160:163], v[200:203], v[20:23]
	v_mfma_f32_16x16x32_bf16 v[16:19], v[168:171], v[200:203], v[16:19]
	v_mfma_f32_16x16x32_bf16 v[4:7], v[160:163], v[208:211], v[4:7]
	v_mfma_f32_16x16x32_bf16 v[0:3], v[168:171], v[208:211], v[0:3]
	v_mfma_f32_16x16x32_bf16 v[52:55], v[164:167], v[186:189], v[52:55]
	v_mfma_f32_16x16x32_bf16 v[48:51], v[172:175], v[186:189], v[48:51]
	v_mfma_f32_16x16x32_bf16 v[36:39], v[164:167], v[196:199], v[36:39]
	v_mfma_f32_16x16x32_bf16 v[32:35], v[172:175], v[196:199], v[32:35]
	v_mfma_f32_16x16x32_bf16 v[20:23], v[164:167], v[204:207], v[20:23]
	v_mfma_f32_16x16x32_bf16 v[16:19], v[172:175], v[204:207], v[16:19]
	v_mfma_f32_16x16x32_bf16 v[4:7], v[164:167], v[212:215], v[4:7]
	v_mfma_f32_16x16x32_bf16 v[0:3], v[172:175], v[212:215], v[0:3]
	s_setprio 0
	s_barrier
	s_add_i32 s53, s53, 2
	s_add_u32 s50, s50, 0x100
	s_addc_u32 s51, s51, 0
	s_cmpk_gt_u32 s53, 0x55
	s_mov_b64 s[26:27], s[28:29]
	s_cbranch_scc0 .LBB0_1030
	s_and_b64 vcc, exec, s[20:21]
	s_cbranch_vccz .LBB0_1033
	s_barrier
